# v25: + dropped the compiler's redundant lgkmcnt(0) after each K-loop barrier (asm wait before the barrier already drains LDS)
# baseline (speedup 1.0000x reference)
; #define PG8_STAGE(bufoff, gbase, voff) do { _Pragma("unroll") for (int _i = 0; _i < 2; ++_i) \
;         __builtin_amdgcn_global_load_lds((const unsigned*)((const char*)(gbase) + (voff)[_i]), (PG8_LAS unsigned*)(lds + (bufoff) + ldsw + _i * 8192), 16, 0, 0); } while (0)
; #define PG8_LDA(dst, b, h) do { _Pragma("unroll") for (int m = 0; m < 4; ++m) _Pragma("unroll") for (int k = 0; k < 2; ++k) dst[m][k] = *(const PG8_LAS bf16x8*)(lds + PG8_SA(b, h) + aoff + m * 2048 + k * 1024); } while (0)
; #define PG8_LDB(dst, b, h) do { _Pragma("unroll") for (int n = 0; n < 2; ++n) _Pragma("unroll") for (int k = 0; k < 2; ++k) dst[n][k] = *(const PG8_LAS bf16x8*)(lds + PG8_SB(b, h) + boff + n * 2048 + k * 1024); } while (0)
; #define PG8_MMA(ai, bj, At, Bt) do { __builtin_amdgcn_s_setprio(1); _Pragma("unroll") for (int m = 0; m < 4; ++m) _Pragma("unroll") for (int n = 0; n < 2; ++n) _Pragma("unroll") for (int k = 0; k < 2; ++k) \
;         acc[ai][bj][m][n] = __builtin_amdgcn_mfma_f32_16x16x32_bf16(Bt[n][k], At[m][k], acc[ai][bj][m][n], 0, 0, 0); __builtin_amdgcn_s_setprio(0); } while (0)
; #define PG8_WAIT_V(n) asm volatile("s_waitcnt vmcnt(" #n ")" ::: "memory")
; #define PG8_WAIT_L(n) asm volatile("s_waitcnt lgkmcnt(" #n ")" ::: "memory")
; template <class Epi, class Sched, bool ALIGN_EPI = false, bool SP2 = false>
; __device__ __forceinline__ void gemm_phase(PG8_LAS unsigned char* lds, const Gemm g, const Sched& S, const Epi& E, const int wave_s) {
;     ...
;             const bool last = (t == nt - 2);
;             const char* a1 = cA + (size_t)(t + 1) * kstep;
;             const char* a2 = last ? nA : cA + (size_t)(t + 2) * kstep; const char* b2 = last ? nB : cB + (size_t)(t + 2) * kstep;
;             const char* a3 = a2 + kstep; const char* b3 = b2 + kstep;
;             if (last && has_next) S.a_ready(nxt);
;             if constexpr (SP2) {
;             PG8_LDB(B0, 0, 0); PG8_LDB(B1, 0, 1); PG8_SCHED; PG8_LDA(At, 0, 0); PG8_STAGE(PG8_SA(1, 1), a1 + hstep, voffA);
;             PG8_WAIT_V(8); PG8_WAIT_L(0); PG8_BAR; PG8_MMA(0, 0, At, B0); PG8_MMA(0, 1, At, B1); PG8_BAR; PG8_SCHED;
;             PG8_LDA(At, 0, 1); PG8_STAGE(PG8_SB(0, 0), b2, voffB); PG8_STAGE(PG8_SB(0, 1), b2 + hstep, voffB); PG8_STAGE(PG8_SA(0, 0), a2, voffA);
;             PG8_WAIT_V(8); PG8_WAIT_L(0); PG8_BAR; PG8_MMA(1, 0, At, B0); PG8_MMA(1, 1, At, B1); PG8_BAR; PG8_SCHED;
.LBB0_219:
	s_add_u32 s34, s30, 0xfffc0080
	s_addc_u32 s35, s31, -1
	s_add_i32 s45, 0, 0x10000
	s_cmp_eq_u32 s68, 12
	s_cselect_b32 s37, s5, s35
	s_cselect_b32 s36, s23, s34
	v_add_u32_e32 v0, s45, v180
	s_cselect_b32 s35, s21, s64
	s_cselect_b32 s34, s29, s55
	s_add_i32 s75, 0, 0x14000
	ds_read_b128 v[78:81], v0
	ds_read_b128 v[86:89], v0 offset:1024
	ds_read_b128 v[98:101], v0 offset:2048
	ds_read_b128 v[102:105], v0 offset:3072
	v_add_u32_e32 v0, s75, v180
	ds_read_b128 v[170:173], v0
	ds_read_b128 v[174:177], v0 offset:1024
	ds_read_b128 v[184:187], v0 offset:2048
	ds_read_b128 v[188:191], v0 offset:3072
	v_lshl_add_u64 v[230:231], s[30:31], 0, v[164:165]
	s_add_i32 m0, s47, 0xc000
	ds_read_b128 v[192:195], v182
	ds_read_b128 v[196:199], v182 offset:1024
	ds_read_b128 v[200:203], v182 offset:2048
	ds_read_b128 v[210:213], v182 offset:3072
	ds_read_b128 v[214:217], v182 offset:4096
	ds_read_b128 v[218:221], v182 offset:5120
	ds_read_b128 v[222:225], v182 offset:6144
	ds_read_b128 v[226:229], v182 offset:7168
	global_load_lds_dwordx4 v[230:231], off
	v_lshl_add_u64 v[230:231], s[30:31], 0, v[166:167]
	s_add_i32 m0, s47, 0xe000
	s_nop 0
	global_load_lds_dwordx4 v[230:231], off
	s_waitcnt vmcnt(8)
	s_waitcnt lgkmcnt(0)
	s_barrier
	s_setprio 1
	v_mfma_f32_16x16x32_bf16 v[142:145], v[78:81], v[192:195], v[142:145]
	v_mfma_f32_16x16x32_bf16 v[138:141], v[98:101], v[192:195], v[138:141]
	v_mfma_f32_16x16x32_bf16 v[126:129], v[78:81], v[200:203], v[126:129]
	v_mfma_f32_16x16x32_bf16 v[122:125], v[98:101], v[200:203], v[122:125]
	v_mfma_f32_16x16x32_bf16 v[110:113], v[78:81], v[214:217], v[110:113]
	v_mfma_f32_16x16x32_bf16 v[106:109], v[98:101], v[214:217], v[106:109]
	v_mfma_f32_16x16x32_bf16 v[82:85], v[78:81], v[222:225], v[82:85]
	v_mfma_f32_16x16x32_bf16 v[74:77], v[98:101], v[222:225], v[74:77]
	v_mfma_f32_16x16x32_bf16 v[142:145], v[86:89], v[196:199], v[142:145]
	v_mfma_f32_16x16x32_bf16 v[138:141], v[102:105], v[196:199], v[138:141]
	v_mfma_f32_16x16x32_bf16 v[126:129], v[86:89], v[210:213], v[126:129]
	v_mfma_f32_16x16x32_bf16 v[122:125], v[102:105], v[210:213], v[122:125]
	v_mfma_f32_16x16x32_bf16 v[110:113], v[86:89], v[218:221], v[110:113]
	v_mfma_f32_16x16x32_bf16 v[106:109], v[102:105], v[218:221], v[106:109]
	v_mfma_f32_16x16x32_bf16 v[82:85], v[86:89], v[226:229], v[82:85]
	v_mfma_f32_16x16x32_bf16 v[74:77], v[102:105], v[226:229], v[74:77]
	s_setprio 0
	s_setprio 1
	v_mfma_f32_16x16x32_bf16 v[134:137], v[170:173], v[192:195], v[134:137]
	v_mfma_f32_16x16x32_bf16 v[130:133], v[184:187], v[192:195], v[130:133]
	v_mfma_f32_16x16x32_bf16 v[118:121], v[170:173], v[200:203], v[118:121]
	v_mfma_f32_16x16x32_bf16 v[114:117], v[184:187], v[200:203], v[114:117]
	v_mfma_f32_16x16x32_bf16 v[94:97], v[170:173], v[214:217], v[94:97]
	v_mfma_f32_16x16x32_bf16 v[90:93], v[184:187], v[214:217], v[90:93]
	v_mfma_f32_16x16x32_bf16 v[70:73], v[170:173], v[222:225], v[70:73]
	v_mfma_f32_16x16x32_bf16 v[66:69], v[184:187], v[222:225], v[66:69]
	v_mfma_f32_16x16x32_bf16 v[134:137], v[174:177], v[196:199], v[134:137]
	v_mfma_f32_16x16x32_bf16 v[130:133], v[188:191], v[196:199], v[130:133]
	v_mfma_f32_16x16x32_bf16 v[118:121], v[174:177], v[210:213], v[118:121]
	v_mfma_f32_16x16x32_bf16 v[114:117], v[188:191], v[210:213], v[114:117]
	v_mfma_f32_16x16x32_bf16 v[94:97], v[174:177], v[218:221], v[94:97]
	v_mfma_f32_16x16x32_bf16 v[90:93], v[188:191], v[218:221], v[90:93]
	v_mfma_f32_16x16x32_bf16 v[70:73], v[174:177], v[226:229], v[70:73]
	v_mfma_f32_16x16x32_bf16 v[66:69], v[188:191], v[226:229], v[66:69]
	s_setprio 0
	s_barrier
	s_add_i32 s45, s45, s44
	v_lshl_add_u64 v[230:231], s[34:35], 0, v[148:149]
	s_mov_b32 m0, s45
	ds_read_b128 v[192:195], v182 offset:16384
	ds_read_b128 v[196:199], v182 offset:17408
	ds_read_b128 v[200:203], v182 offset:18432
	ds_read_b128 v[210:213], v182 offset:19456
	ds_read_b128 v[214:217], v182 offset:20480
	ds_read_b128 v[218:221], v182 offset:21504
	ds_read_b128 v[222:225], v182 offset:22528
	ds_read_b128 v[226:229], v182 offset:23552
	global_load_lds_dwordx4 v[230:231], off
	s_add_i32 m0, s45, 0x2000
	s_add_u32 s80, s34, 0x40000
	v_lshl_add_u64 v[232:233], s[34:35], 0, v[152:153]
	s_addc_u32 s81, s35, 0
	s_add_i32 s45, s75, s44
	global_load_lds_dwordx4 v[232:233], off
	v_lshl_add_u64 v[234:235], s[80:81], 0, v[148:149]
	s_mov_b32 m0, s45
	v_lshl_add_u64 v[236:237], s[36:37], 0, v[150:151]
	global_load_lds_dwordx4 v[234:235], off
	v_lshl_add_u64 v[234:235], s[80:81], 0, v[152:153]
	s_add_i32 m0, s45, 0x2000
	s_nop 0
	global_load_lds_dwordx4 v[234:235], off
	v_lshl_add_u64 v[234:235], s[36:37], 0, v[146:147]
	s_mov_b32 m0, s47
	s_nop 0
	global_load_lds_dwordx4 v[234:235], off
	s_mov_b32 m0, s48
	s_nop 0
	global_load_lds_dwordx4 v[236:237], off
	s_waitcnt vmcnt(8)
	s_waitcnt lgkmcnt(0)
	s_barrier
; #define PG8_STAGE(bufoff, gbase, voff) do { _Pragma("unroll") for (int _i = 0; _i < 2; ++_i) \
;         __builtin_amdgcn_global_load_lds((const unsigned*)((const char*)(gbase) + (voff)[_i]), (PG8_LAS unsigned*)(lds + (bufoff) + ldsw + _i * 8192), 16, 0, 0); } while (0)
; #define PG8_LDA(dst, b, h) do { _Pragma("unroll") for (int m = 0; m < 4; ++m) _Pragma("unroll") for (int k = 0; k < 2; ++k) dst[m][k] = *(const PG8_LAS bf16x8*)(lds + PG8_SA(b, h) + aoff + m * 2048 + k * 1024); } while (0)
; #define PG8_LDB(dst, b, h) do { _Pragma("unroll") for (int n = 0; n < 2; ++n) _Pragma("unroll") for (int k = 0; k < 2; ++k) dst[n][k] = *(const PG8_LAS bf16x8*)(lds + PG8_SB(b, h) + boff + n * 2048 + k * 1024); } while (0)
; #define PG8_MMA(ai, bj, At, Bt) do { __builtin_amdgcn_s_setprio(1); _Pragma("unroll") for (int m = 0; m < 4; ++m) _Pragma("unroll") for (int n = 0; n < 2; ++n) _Pragma("unroll") for (int k = 0; k < 2; ++k) \
;         acc[ai][bj][m][n] = __builtin_amdgcn_mfma_f32_16x16x32_bf16(Bt[n][k], At[m][k], acc[ai][bj][m][n], 0, 0, 0); __builtin_amdgcn_s_setprio(0); } while (0)
; #define PG8_WAIT_V(n) asm volatile("s_waitcnt vmcnt(" #n ")" ::: "memory")
; #define PG8_WAIT_L(n) asm volatile("s_waitcnt lgkmcnt(" #n ")" ::: "memory")
; #define PG8_BAR __builtin_amdgcn_s_barrier()
; #define PG8_SCHED __builtin_amdgcn_sched_barrier(0)
; template <class Epi, class Sched, bool ALIGN_EPI = false, bool SP2 = false>
; __device__ __forceinline__ void gemm_phase(PG8_LAS unsigned char* lds, const Gemm g, const Sched& S, const Epi& E, const int wave_s) {
;     ...
;             PG8_WAIT_V(8); PG8_WAIT_L(0); PG8_BAR; PG8_MMA(1, 0, At, B0); PG8_MMA(1, 1, At, B1); PG8_BAR; PG8_SCHED;
;             PG8_LDB(B0, 1, 0); PG8_LDB(B1, 1, 1); PG8_SCHED; PG8_LDA(At, 1, 0); PG8_STAGE(PG8_SA(0, 1), a2 + hstep, voffA);
;             PG8_WAIT_V(8); PG8_WAIT_L(0); PG8_BAR; PG8_MMA(0, 0, At, B0); PG8_MMA(0, 1, At, B1); PG8_BAR; PG8_SCHED;
	s_setprio 1
	v_mfma_f32_16x16x32_bf16 v[62:65], v[78:81], v[192:195], v[62:65]
	v_mfma_f32_16x16x32_bf16 v[58:61], v[98:101], v[192:195], v[58:61]
	v_mfma_f32_16x16x32_bf16 v[46:49], v[78:81], v[200:203], v[46:49]
	v_mfma_f32_16x16x32_bf16 v[42:45], v[98:101], v[200:203], v[42:45]
	v_mfma_f32_16x16x32_bf16 v[30:33], v[78:81], v[214:217], v[30:33]
	v_mfma_f32_16x16x32_bf16 v[26:29], v[98:101], v[214:217], v[26:29]
	v_mfma_f32_16x16x32_bf16 v[14:17], v[78:81], v[222:225], v[14:17]
	v_mfma_f32_16x16x32_bf16 v[10:13], v[98:101], v[222:225], v[10:13]
	v_mfma_f32_16x16x32_bf16 v[62:65], v[86:89], v[196:199], v[62:65]
	v_mfma_f32_16x16x32_bf16 v[58:61], v[102:105], v[196:199], v[58:61]
	v_mfma_f32_16x16x32_bf16 v[46:49], v[86:89], v[210:213], v[46:49]
	v_mfma_f32_16x16x32_bf16 v[42:45], v[102:105], v[210:213], v[42:45]
	v_mfma_f32_16x16x32_bf16 v[30:33], v[86:89], v[218:221], v[30:33]
	v_mfma_f32_16x16x32_bf16 v[26:29], v[102:105], v[218:221], v[26:29]
	v_mfma_f32_16x16x32_bf16 v[14:17], v[86:89], v[226:229], v[14:17]
	v_mfma_f32_16x16x32_bf16 v[10:13], v[102:105], v[226:229], v[10:13]
	s_setprio 0
	s_setprio 1
	v_mfma_f32_16x16x32_bf16 v[54:57], v[170:173], v[192:195], v[54:57]
	v_mfma_f32_16x16x32_bf16 v[50:53], v[184:187], v[192:195], v[50:53]
	v_mfma_f32_16x16x32_bf16 v[38:41], v[170:173], v[200:203], v[38:41]
	v_mfma_f32_16x16x32_bf16 v[34:37], v[184:187], v[200:203], v[34:37]
	v_mfma_f32_16x16x32_bf16 v[22:25], v[170:173], v[214:217], v[22:25]
	v_mfma_f32_16x16x32_bf16 v[18:21], v[184:187], v[214:217], v[18:21]
	v_mfma_f32_16x16x32_bf16 v[6:9], v[170:173], v[222:225], v[6:9]
	v_mfma_f32_16x16x32_bf16 v[2:5], v[184:187], v[222:225], v[2:5]
	v_mfma_f32_16x16x32_bf16 v[54:57], v[174:177], v[196:199], v[54:57]
	v_mfma_f32_16x16x32_bf16 v[50:53], v[188:191], v[196:199], v[50:53]
	v_mfma_f32_16x16x32_bf16 v[38:41], v[174:177], v[210:213], v[38:41]
	v_mfma_f32_16x16x32_bf16 v[34:37], v[188:191], v[210:213], v[34:37]
	v_mfma_f32_16x16x32_bf16 v[22:25], v[174:177], v[218:221], v[22:25]
	v_mfma_f32_16x16x32_bf16 v[18:21], v[188:191], v[218:221], v[18:21]
	v_mfma_f32_16x16x32_bf16 v[6:9], v[174:177], v[226:229], v[6:9]
	v_mfma_f32_16x16x32_bf16 v[2:5], v[188:191], v[226:229], v[2:5]
	s_setprio 0
	s_barrier
	s_add_i32 s45, 0, 0x18000
	v_add_u32_e32 v0, s45, v180
	s_add_i32 s75, 0, 0x1c000
	ds_read_b128 v[78:81], v0
	ds_read_b128 v[86:89], v0 offset:1024
	ds_read_b128 v[98:101], v0 offset:2048
	ds_read_b128 v[102:105], v0 offset:3072
	v_add_u32_e32 v0, s75, v180
	ds_read_b128 v[170:173], v0
	ds_read_b128 v[174:177], v0 offset:1024
	ds_read_b128 v[184:187], v0 offset:2048
	ds_read_b128 v[188:191], v0 offset:3072
	s_add_u32 s36, s36, 0x40000
	s_addc_u32 s37, s37, 0
	s_mov_b32 m0, s49
	v_lshl_add_u64 v[238:239], s[36:37], 0, v[146:147]
	ds_read_b128 v[192:195], v182 offset:32768
	ds_read_b128 v[196:199], v182 offset:33792
	ds_read_b128 v[200:203], v182 offset:34816
	ds_read_b128 v[210:213], v182 offset:35840
	ds_read_b128 v[214:217], v182 offset:36864
	ds_read_b128 v[218:221], v182 offset:37888
	ds_read_b128 v[222:225], v182 offset:38912
	ds_read_b128 v[226:229], v182 offset:39936
	global_load_lds_dwordx4 v[238:239], off
	v_lshl_add_u64 v[238:239], s[36:37], 0, v[150:151]
	s_mov_b32 m0, s50
	s_nop 0
	global_load_lds_dwordx4 v[238:239], off
	s_waitcnt vmcnt(8)
	s_waitcnt lgkmcnt(0)
	s_barrier
	s_setprio 1
	v_mfma_f32_16x16x32_bf16 v[142:145], v[78:81], v[192:195], v[142:145]
	v_mfma_f32_16x16x32_bf16 v[138:141], v[98:101], v[192:195], v[138:141]
	v_mfma_f32_16x16x32_bf16 v[126:129], v[78:81], v[200:203], v[126:129]
	v_mfma_f32_16x16x32_bf16 v[122:125], v[98:101], v[200:203], v[122:125]
	v_mfma_f32_16x16x32_bf16 v[110:113], v[78:81], v[214:217], v[110:113]
	v_mfma_f32_16x16x32_bf16 v[106:109], v[98:101], v[214:217], v[106:109]
	v_mfma_f32_16x16x32_bf16 v[82:85], v[78:81], v[222:225], v[82:85]
	v_mfma_f32_16x16x32_bf16 v[74:77], v[98:101], v[222:225], v[74:77]
	v_mfma_f32_16x16x32_bf16 v[142:145], v[86:89], v[196:199], v[142:145]
	v_mfma_f32_16x16x32_bf16 v[138:141], v[102:105], v[196:199], v[138:141]
	v_mfma_f32_16x16x32_bf16 v[126:129], v[86:89], v[210:213], v[126:129]
	v_mfma_f32_16x16x32_bf16 v[122:125], v[102:105], v[210:213], v[122:125]
	v_mfma_f32_16x16x32_bf16 v[110:113], v[86:89], v[218:221], v[110:113]
	v_mfma_f32_16x16x32_bf16 v[106:109], v[102:105], v[218:221], v[106:109]
	v_mfma_f32_16x16x32_bf16 v[82:85], v[86:89], v[226:229], v[82:85]
	v_mfma_f32_16x16x32_bf16 v[74:77], v[102:105], v[226:229], v[74:77]
	s_setprio 0
	s_setprio 1
	v_mfma_f32_16x16x32_bf16 v[134:137], v[170:173], v[192:195], v[134:137]
	v_mfma_f32_16x16x32_bf16 v[130:133], v[184:187], v[192:195], v[130:133]
	v_mfma_f32_16x16x32_bf16 v[118:121], v[170:173], v[200:203], v[118:121]
	v_mfma_f32_16x16x32_bf16 v[114:117], v[184:187], v[200:203], v[114:117]
	v_mfma_f32_16x16x32_bf16 v[94:97], v[170:173], v[214:217], v[94:97]
	v_mfma_f32_16x16x32_bf16 v[90:93], v[184:187], v[214:217], v[90:93]
	v_mfma_f32_16x16x32_bf16 v[70:73], v[170:173], v[222:225], v[70:73]
	v_mfma_f32_16x16x32_bf16 v[66:69], v[184:187], v[222:225], v[66:69]
	v_mfma_f32_16x16x32_bf16 v[134:137], v[174:177], v[196:199], v[134:137]
	v_mfma_f32_16x16x32_bf16 v[130:133], v[188:191], v[196:199], v[130:133]
	v_mfma_f32_16x16x32_bf16 v[118:121], v[174:177], v[210:213], v[118:121]
	v_mfma_f32_16x16x32_bf16 v[114:117], v[188:191], v[210:213], v[114:117]
	v_mfma_f32_16x16x32_bf16 v[94:97], v[174:177], v[218:221], v[94:97]
	v_mfma_f32_16x16x32_bf16 v[90:93], v[188:191], v[218:221], v[90:93]
	v_mfma_f32_16x16x32_bf16 v[70:73], v[174:177], v[226:229], v[70:73]
	v_mfma_f32_16x16x32_bf16 v[66:69], v[188:191], v[226:229], v[66:69]
	s_setprio 0
	s_barrier
; #define PG8_STAGE(bufoff, gbase, voff) do { _Pragma("unroll") for (int _i = 0; _i < 2; ++_i) \
;         __builtin_amdgcn_global_load_lds((const unsigned*)((const char*)(gbase) + (voff)[_i]), (PG8_LAS unsigned*)(lds + (bufoff) + ldsw + _i * 8192), 16, 0, 0); } while (0)
; #define PG8_LDA(dst, b, h) do { _Pragma("unroll") for (int m = 0; m < 4; ++m) _Pragma("unroll") for (int k = 0; k < 2; ++k) dst[m][k] = *(const PG8_LAS bf16x8*)(lds + PG8_SA(b, h) + aoff + m * 2048 + k * 1024); } while (0)
; #define PG8_BAR __builtin_amdgcn_s_barrier()
; template <class Epi, class Sched, bool ALIGN_EPI = false, bool SP2 = false>
; __device__ __forceinline__ void gemm_phase(PG8_LAS unsigned char* lds, const Gemm g, const Sched& S, const Epi& E, const int wave_s) {
;     ...
;             PG8_LDA(At, 1, 1); PG8_STAGE(PG8_SB(1, 0), b3, voffB); PG8_STAGE(PG8_SB(1, 1), b3 + hstep, voffB); PG8_STAGE(PG8_SA(1, 0), a3, voffA);
;             PG8_WAIT_V(8); PG8_WAIT_L(0); PG8_BAR; PG8_MMA(1, 0, At, B0); PG8_MMA(1, 1, At, B1); PG8_BAR; PG8_SCHED;
;             } else {
;             PG8_LDB(B0, 0, 0); PG8_SCHED; PG8_LDA(At, 0, 0); PG8_STAGE(PG8_SA(1, 1), a1 + hstep, voffA);
;             PG8_WAIT_L(8); PG8_BAR; PG8_WAIT_L(0); PG8_MMA(0, 0, At, B0); PG8_BAR; PG8_SCHED;
;             PG8_LDB(B1, 0, 1); PG8_STAGE(PG8_SB(0, 0), b2, voffB);
;             PG8_BAR; PG8_WAIT_L(0); PG8_MMA(0, 1, At, B1); PG8_BAR;
;             PG8_LDA(At, 0, 1); PG8_STAGE(PG8_SA(0, 0), a2, voffA);
;             PG8_BAR; PG8_WAIT_L(0); PG8_MMA(1, 0, At, B0); PG8_BAR; PG8_SCHED;
;             PG8_STAGE(PG8_SB(0, 1), b2 + hstep, voffB);
;             PG8_WAIT_V(6); PG8_BAR; PG8_MMA(1, 1, At, B1); PG8_BAR;
;             PG8_LDB(B0, 1, 0); PG8_SCHED; PG8_LDA(At, 1, 0); PG8_STAGE(PG8_SA(0, 1), a2 + hstep, voffA);
;             PG8_WAIT_L(8); PG8_BAR; PG8_WAIT_L(0); PG8_MMA(0, 0, At, B0); PG8_BAR; PG8_SCHED;
;             PG8_LDB(B1, 1, 1); PG8_STAGE(PG8_SB(1, 0), b3, voffB);
;             PG8_BAR; PG8_WAIT_L(0); PG8_MMA(0, 1, At, B1); PG8_BAR;
;             PG8_LDA(At, 1, 1); PG8_STAGE(PG8_SA(1, 0), a3, voffA);
;             PG8_BAR; PG8_WAIT_L(0); PG8_MMA(1, 0, At, B0); PG8_BAR; PG8_SCHED;
;             PG8_STAGE(PG8_SB(1, 1), b3 + hstep, voffB);
;             PG8_WAIT_V(6); PG8_BAR; PG8_MMA(1, 1, At, B1); PG8_BAR;
;             }
;         }
;         if constexpr (ALIGN_EPI) { if (wr == 0) PG8_BAR; }
	s_add_i32 s36, s45, s44
	v_lshl_add_u64 v[230:231], v[230:231], 0, s[70:71]
	s_mov_b32 m0, s36
	ds_read_b128 v[192:195], v182 offset:49152
	ds_read_b128 v[196:199], v182 offset:50176
	ds_read_b128 v[200:203], v182 offset:51200
	ds_read_b128 v[210:213], v182 offset:52224
	ds_read_b128 v[214:217], v182 offset:53248
	ds_read_b128 v[218:221], v182 offset:54272
	ds_read_b128 v[222:225], v182 offset:55296
	ds_read_b128 v[226:229], v182 offset:56320
	global_load_lds_dwordx4 v[230:231], off
	s_add_i32 m0, s36, 0x2000
	s_add_u32 s34, s34, 0x40080
	v_lshl_add_u64 v[230:231], v[232:233], 0, s[70:71]
	s_addc_u32 s35, s35, 0
	s_add_i32 s36, s75, s44
	global_load_lds_dwordx4 v[230:231], off
	v_lshl_add_u64 v[230:231], s[34:35], 0, v[148:149]
	s_mov_b32 m0, s36
	s_nop 0
	global_load_lds_dwordx4 v[230:231], off
	v_lshl_add_u64 v[230:231], s[34:35], 0, v[152:153]
	s_add_i32 m0, s36, 0x2000
	s_nop 0
	global_load_lds_dwordx4 v[230:231], off
	v_lshl_add_u64 v[230:231], v[234:235], 0, s[70:71]
	s_mov_b32 m0, s58
	s_nop 0
	global_load_lds_dwordx4 v[230:231], off
	v_lshl_add_u64 v[230:231], v[236:237], 0, s[70:71]
	s_mov_b32 m0, s59
	s_nop 0
	global_load_lds_dwordx4 v[230:231], off
	s_waitcnt vmcnt(8)
	s_waitcnt lgkmcnt(0)
	s_barrier
	s_setprio 1
	v_mfma_f32_16x16x32_bf16 v[62:65], v[78:81], v[192:195], v[62:65]
	v_mfma_f32_16x16x32_bf16 v[58:61], v[98:101], v[192:195], v[58:61]
	v_mfma_f32_16x16x32_bf16 v[46:49], v[78:81], v[200:203], v[46:49]
	v_mfma_f32_16x16x32_bf16 v[42:45], v[98:101], v[200:203], v[42:45]
	v_mfma_f32_16x16x32_bf16 v[30:33], v[78:81], v[214:217], v[30:33]
	v_mfma_f32_16x16x32_bf16 v[26:29], v[98:101], v[214:217], v[26:29]
	v_mfma_f32_16x16x32_bf16 v[14:17], v[78:81], v[222:225], v[14:17]
	v_mfma_f32_16x16x32_bf16 v[10:13], v[98:101], v[222:225], v[10:13]
	v_mfma_f32_16x16x32_bf16 v[62:65], v[86:89], v[196:199], v[62:65]
	v_mfma_f32_16x16x32_bf16 v[58:61], v[102:105], v[196:199], v[58:61]
	v_mfma_f32_16x16x32_bf16 v[46:49], v[86:89], v[210:213], v[46:49]
	v_mfma_f32_16x16x32_bf16 v[42:45], v[102:105], v[210:213], v[42:45]
	v_mfma_f32_16x16x32_bf16 v[30:33], v[86:89], v[218:221], v[30:33]
	v_mfma_f32_16x16x32_bf16 v[26:29], v[102:105], v[218:221], v[26:29]
	v_mfma_f32_16x16x32_bf16 v[14:17], v[86:89], v[226:229], v[14:17]
	v_mfma_f32_16x16x32_bf16 v[10:13], v[102:105], v[226:229], v[10:13]
	s_setprio 0
	s_setprio 1
	v_mfma_f32_16x16x32_bf16 v[54:57], v[170:173], v[192:195], v[54:57]
	v_mfma_f32_16x16x32_bf16 v[50:53], v[184:187], v[192:195], v[50:53]
	v_mfma_f32_16x16x32_bf16 v[38:41], v[170:173], v[200:203], v[38:41]
	v_mfma_f32_16x16x32_bf16 v[34:37], v[184:187], v[200:203], v[34:37]
	v_mfma_f32_16x16x32_bf16 v[22:25], v[170:173], v[214:217], v[22:25]
	v_mfma_f32_16x16x32_bf16 v[18:21], v[184:187], v[214:217], v[18:21]
	v_mfma_f32_16x16x32_bf16 v[6:9], v[170:173], v[222:225], v[6:9]
	v_mfma_f32_16x16x32_bf16 v[2:5], v[184:187], v[222:225], v[2:5]
	v_mfma_f32_16x16x32_bf16 v[54:57], v[174:177], v[196:199], v[54:57]
	v_mfma_f32_16x16x32_bf16 v[50:53], v[188:191], v[196:199], v[50:53]
	v_mfma_f32_16x16x32_bf16 v[38:41], v[174:177], v[210:213], v[38:41]
	v_mfma_f32_16x16x32_bf16 v[34:37], v[188:191], v[210:213], v[34:37]
	v_mfma_f32_16x16x32_bf16 v[22:25], v[174:177], v[218:221], v[22:25]
	v_mfma_f32_16x16x32_bf16 v[18:21], v[188:191], v[218:221], v[18:21]
	v_mfma_f32_16x16x32_bf16 v[6:9], v[174:177], v[226:229], v[6:9]
	v_mfma_f32_16x16x32_bf16 v[2:5], v[188:191], v[226:229], v[2:5]
	s_setprio 0
	s_barrier
	s_add_i32 s68, s68, 2
	s_add_u32 s30, s30, 0x100
	s_addc_u32 s31, s31, 0
	s_add_u32 s55, s55, 0x100
	s_addc_u32 s64, s64, 0
	s_cmp_gt_u32 s68, 13
	s_cbranch_scc0 .LBB0_219
	s_and_b64 vcc, exec, s[18:19]
	s_cbranch_vccz .LBB0_222
	s_barrier

; #define PG8_STAGE(bufoff, gbase, voff) do { _Pragma("unroll") for (int _i = 0; _i < 2; ++_i) \
;         __builtin_amdgcn_global_load_lds((const unsigned*)((const char*)(gbase) + (voff)[_i]), (PG8_LAS unsigned*)(lds + (bufoff) + ldsw + _i * 8192), 16, 0, 0); } while (0)
; #define PG8_LDA(dst, b, h) do { _Pragma("unroll") for (int m = 0; m < 4; ++m) _Pragma("unroll") for (int k = 0; k < 2; ++k) dst[m][k] = *(const PG8_LAS bf16x8*)(lds + PG8_SA(b, h) + aoff + m * 2048 + k * 1024); } while (0)
; #define PG8_LDB(dst, b, h) do { _Pragma("unroll") for (int n = 0; n < 2; ++n) _Pragma("unroll") for (int k = 0; k < 2; ++k) dst[n][k] = *(const PG8_LAS bf16x8*)(lds + PG8_SB(b, h) + boff + n * 2048 + k * 1024); } while (0)
; #define PG8_MMA(ai, bj, At, Bt) do { __builtin_amdgcn_s_setprio(1); _Pragma("unroll") for (int m = 0; m < 4; ++m) _Pragma("unroll") for (int n = 0; n < 2; ++n) _Pragma("unroll") for (int k = 0; k < 2; ++k) \
;         acc[ai][bj][m][n] = __builtin_amdgcn_mfma_f32_16x16x32_bf16(Bt[n][k], At[m][k], acc[ai][bj][m][n], 0, 0, 0); __builtin_amdgcn_s_setprio(0); } while (0)
; #define PG8_WAIT_V(n) asm volatile("s_waitcnt vmcnt(" #n ")" ::: "memory")
; #define PG8_WAIT_L(n) asm volatile("s_waitcnt lgkmcnt(" #n ")" ::: "memory")
; template <class Epi, class Sched, bool ALIGN_EPI = false, bool SP2 = false>
; __device__ __forceinline__ void gemm_phase(PG8_LAS unsigned char* lds, const Gemm g, const Sched& S, const Epi& E, const int wave_s) {
;     ...
;             const bool last = (t == nt - 2);
;             const char* a1 = cA + (size_t)(t + 1) * kstep;
;             const char* a2 = last ? nA : cA + (size_t)(t + 2) * kstep; const char* b2 = last ? nB : cB + (size_t)(t + 2) * kstep;
;             const char* a3 = a2 + kstep; const char* b3 = b2 + kstep;
;             if (last && has_next) S.a_ready(nxt);
;             if constexpr (SP2) {
;             PG8_LDB(B0, 0, 0); PG8_LDB(B1, 0, 1); PG8_SCHED; PG8_LDA(At, 0, 0); PG8_STAGE(PG8_SA(1, 1), a1 + hstep, voffA);
;             PG8_WAIT_V(8); PG8_WAIT_L(0); PG8_BAR; PG8_MMA(0, 0, At, B0); PG8_MMA(0, 1, At, B1); PG8_BAR; PG8_SCHED;
;             PG8_LDA(At, 0, 1); PG8_STAGE(PG8_SB(0, 0), b2, voffB); PG8_STAGE(PG8_SB(0, 1), b2 + hstep, voffB); PG8_STAGE(PG8_SA(0, 0), a2, voffA);
;             PG8_WAIT_V(8); PG8_WAIT_L(0); PG8_BAR; PG8_MMA(1, 0, At, B0); PG8_MMA(1, 1, At, B1); PG8_BAR; PG8_SCHED;
.LBB0_325:
	s_add_u32 s30, s28, 0xfffc0080
	s_addc_u32 s31, s29, -1
	s_add_i32 s45, 0, 0x10000
	s_cmp_eq_u32 s68, 12
	s_cselect_b32 s35, s19, s31
	s_cselect_b32 s34, s25, s30
	v_add_u32_e32 v0, s45, v181
	s_cselect_b32 s31, s17, s65
	s_cselect_b32 s30, s55, s64
	s_add_i32 s75, 0, 0x14000
	ds_read_b128 v[130:133], v0
	ds_read_b128 v[134:137], v0 offset:1024
	ds_read_b128 v[138:141], v0 offset:2048
	ds_read_b128 v[142:145], v0 offset:3072
	v_add_u32_e32 v0, s75, v181
	ds_read_b128 v[172:175], v0
	ds_read_b128 v[176:179], v0 offset:1024
	ds_read_b128 v[186:189], v0 offset:2048
	ds_read_b128 v[190:193], v0 offset:3072
	v_lshl_add_u64 v[202:203], s[28:29], 0, v[168:169]
	s_add_i32 m0, s27, 0xc000
	ds_read_b128 v[194:197], v185
	ds_read_b128 v[198:201], v185 offset:1024
	ds_read_b128 v[210:213], v185 offset:2048
	ds_read_b128 v[214:217], v185 offset:3072
	ds_read_b128 v[218:221], v185 offset:4096
	ds_read_b128 v[222:225], v185 offset:5120
	ds_read_b128 v[226:229], v185 offset:6144
	ds_read_b128 v[230:233], v185 offset:7168
	global_load_lds_dwordx4 v[202:203], off
	v_lshl_add_u64 v[202:203], s[28:29], 0, v[170:171]
	s_add_i32 m0, s27, 0xe000
	s_nop 0
	global_load_lds_dwordx4 v[202:203], off
	s_waitcnt vmcnt(8)
	s_waitcnt lgkmcnt(0)
	s_barrier
	s_setprio 1
	v_mfma_f32_16x16x32_bf16 v[126:129], v[130:133], v[194:197], v[126:129]
	v_mfma_f32_16x16x32_bf16 v[122:125], v[138:141], v[194:197], v[122:125]
	v_mfma_f32_16x16x32_bf16 v[110:113], v[130:133], v[210:213], v[110:113]
	v_mfma_f32_16x16x32_bf16 v[106:109], v[138:141], v[210:213], v[106:109]
	v_mfma_f32_16x16x32_bf16 v[94:97], v[130:133], v[218:221], v[94:97]
	v_mfma_f32_16x16x32_bf16 v[90:93], v[138:141], v[218:221], v[90:93]
	v_mfma_f32_16x16x32_bf16 v[78:81], v[130:133], v[226:229], v[78:81]
	v_mfma_f32_16x16x32_bf16 v[74:77], v[138:141], v[226:229], v[74:77]
	v_mfma_f32_16x16x32_bf16 v[126:129], v[134:137], v[198:201], v[126:129]
	v_mfma_f32_16x16x32_bf16 v[122:125], v[142:145], v[198:201], v[122:125]
	v_mfma_f32_16x16x32_bf16 v[110:113], v[134:137], v[214:217], v[110:113]
	v_mfma_f32_16x16x32_bf16 v[106:109], v[142:145], v[214:217], v[106:109]
	v_mfma_f32_16x16x32_bf16 v[94:97], v[134:137], v[222:225], v[94:97]
	v_mfma_f32_16x16x32_bf16 v[90:93], v[142:145], v[222:225], v[90:93]
	v_mfma_f32_16x16x32_bf16 v[78:81], v[134:137], v[230:233], v[78:81]
	v_mfma_f32_16x16x32_bf16 v[74:77], v[142:145], v[230:233], v[74:77]
	s_setprio 0
	s_setprio 1
	v_mfma_f32_16x16x32_bf16 v[118:121], v[172:175], v[194:197], v[118:121]
	v_mfma_f32_16x16x32_bf16 v[114:117], v[186:189], v[194:197], v[114:117]
	v_mfma_f32_16x16x32_bf16 v[102:105], v[172:175], v[210:213], v[102:105]
	v_mfma_f32_16x16x32_bf16 v[98:101], v[186:189], v[210:213], v[98:101]
	v_mfma_f32_16x16x32_bf16 v[86:89], v[172:175], v[218:221], v[86:89]
	v_mfma_f32_16x16x32_bf16 v[82:85], v[186:189], v[218:221], v[82:85]
	v_mfma_f32_16x16x32_bf16 v[70:73], v[172:175], v[226:229], v[70:73]
	v_mfma_f32_16x16x32_bf16 v[66:69], v[186:189], v[226:229], v[66:69]
	v_mfma_f32_16x16x32_bf16 v[118:121], v[176:179], v[198:201], v[118:121]
	v_mfma_f32_16x16x32_bf16 v[114:117], v[190:193], v[198:201], v[114:117]
	v_mfma_f32_16x16x32_bf16 v[102:105], v[176:179], v[214:217], v[102:105]
	v_mfma_f32_16x16x32_bf16 v[98:101], v[190:193], v[214:217], v[98:101]
	v_mfma_f32_16x16x32_bf16 v[86:89], v[176:179], v[222:225], v[86:89]
	v_mfma_f32_16x16x32_bf16 v[82:85], v[190:193], v[222:225], v[82:85]
	v_mfma_f32_16x16x32_bf16 v[70:73], v[176:179], v[230:233], v[70:73]
	v_mfma_f32_16x16x32_bf16 v[66:69], v[190:193], v[230:233], v[66:69]
	s_setprio 0
	s_barrier
	s_add_i32 s45, s45, s44
	v_lshl_add_u64 v[202:203], s[30:31], 0, v[148:149]
	s_mov_b32 m0, s45
	ds_read_b128 v[194:197], v185 offset:16384
	ds_read_b128 v[198:201], v185 offset:17408
	ds_read_b128 v[210:213], v185 offset:18432
	ds_read_b128 v[214:217], v185 offset:19456
	ds_read_b128 v[218:221], v185 offset:20480
	ds_read_b128 v[222:225], v185 offset:21504
	ds_read_b128 v[226:229], v185 offset:22528
	ds_read_b128 v[230:233], v185 offset:23552
	global_load_lds_dwordx4 v[202:203], off
	s_add_i32 m0, s45, 0x2000
	s_add_u32 s80, s30, 0x40000
	v_lshl_add_u64 v[234:235], s[30:31], 0, v[152:153]
	s_addc_u32 s81, s31, 0
	s_add_i32 s45, s75, s44
	global_load_lds_dwordx4 v[234:235], off
	v_lshl_add_u64 v[236:237], s[80:81], 0, v[148:149]
	s_mov_b32 m0, s45
	v_lshl_add_u64 v[238:239], s[34:35], 0, v[150:151]
	global_load_lds_dwordx4 v[236:237], off
	v_lshl_add_u64 v[236:237], s[80:81], 0, v[152:153]
	s_add_i32 m0, s45, 0x2000
	s_nop 0
	global_load_lds_dwordx4 v[236:237], off
	v_lshl_add_u64 v[236:237], s[34:35], 0, v[146:147]
	s_mov_b32 m0, s27
	s_nop 0
	global_load_lds_dwordx4 v[236:237], off
	s_mov_b32 m0, s47
	s_nop 0
	global_load_lds_dwordx4 v[238:239], off
	s_waitcnt vmcnt(8)
	s_waitcnt lgkmcnt(0)
	s_barrier
; #define PG8_STAGE(bufoff, gbase, voff) do { _Pragma("unroll") for (int _i = 0; _i < 2; ++_i) \
;         __builtin_amdgcn_global_load_lds((const unsigned*)((const char*)(gbase) + (voff)[_i]), (PG8_LAS unsigned*)(lds + (bufoff) + ldsw + _i * 8192), 16, 0, 0); } while (0)
; #define PG8_LDA(dst, b, h) do { _Pragma("unroll") for (int m = 0; m < 4; ++m) _Pragma("unroll") for (int k = 0; k < 2; ++k) dst[m][k] = *(const PG8_LAS bf16x8*)(lds + PG8_SA(b, h) + aoff + m * 2048 + k * 1024); } while (0)
; #define PG8_LDB(dst, b, h) do { _Pragma("unroll") for (int n = 0; n < 2; ++n) _Pragma("unroll") for (int k = 0; k < 2; ++k) dst[n][k] = *(const PG8_LAS bf16x8*)(lds + PG8_SB(b, h) + boff + n * 2048 + k * 1024); } while (0)
; #define PG8_MMA(ai, bj, At, Bt) do { __builtin_amdgcn_s_setprio(1); _Pragma("unroll") for (int m = 0; m < 4; ++m) _Pragma("unroll") for (int n = 0; n < 2; ++n) _Pragma("unroll") for (int k = 0; k < 2; ++k) \
;         acc[ai][bj][m][n] = __builtin_amdgcn_mfma_f32_16x16x32_bf16(Bt[n][k], At[m][k], acc[ai][bj][m][n], 0, 0, 0); __builtin_amdgcn_s_setprio(0); } while (0)
; #define PG8_WAIT_V(n) asm volatile("s_waitcnt vmcnt(" #n ")" ::: "memory")
; #define PG8_WAIT_L(n) asm volatile("s_waitcnt lgkmcnt(" #n ")" ::: "memory")
; #define PG8_BAR __builtin_amdgcn_s_barrier()
; #define PG8_SCHED __builtin_amdgcn_sched_barrier(0)
; template <class Epi, class Sched, bool ALIGN_EPI = false, bool SP2 = false>
; __device__ __forceinline__ void gemm_phase(PG8_LAS unsigned char* lds, const Gemm g, const Sched& S, const Epi& E, const int wave_s) {
;     ...
;             PG8_WAIT_V(8); PG8_WAIT_L(0); PG8_BAR; PG8_MMA(1, 0, At, B0); PG8_MMA(1, 1, At, B1); PG8_BAR; PG8_SCHED;
;             PG8_LDB(B0, 1, 0); PG8_LDB(B1, 1, 1); PG8_SCHED; PG8_LDA(At, 1, 0); PG8_STAGE(PG8_SA(0, 1), a2 + hstep, voffA);
;             PG8_WAIT_V(8); PG8_WAIT_L(0); PG8_BAR; PG8_MMA(0, 0, At, B0); PG8_MMA(0, 1, At, B1); PG8_BAR; PG8_SCHED;
	s_setprio 1
	v_mfma_f32_16x16x32_bf16 v[62:65], v[130:133], v[194:197], v[62:65]
	v_mfma_f32_16x16x32_bf16 v[58:61], v[138:141], v[194:197], v[58:61]
	v_mfma_f32_16x16x32_bf16 v[46:49], v[130:133], v[210:213], v[46:49]
	v_mfma_f32_16x16x32_bf16 v[42:45], v[138:141], v[210:213], v[42:45]
	v_mfma_f32_16x16x32_bf16 v[30:33], v[130:133], v[218:221], v[30:33]
	v_mfma_f32_16x16x32_bf16 v[26:29], v[138:141], v[218:221], v[26:29]
	v_mfma_f32_16x16x32_bf16 v[14:17], v[130:133], v[226:229], v[14:17]
	v_mfma_f32_16x16x32_bf16 v[10:13], v[138:141], v[226:229], v[10:13]
	v_mfma_f32_16x16x32_bf16 v[62:65], v[134:137], v[198:201], v[62:65]
	v_mfma_f32_16x16x32_bf16 v[58:61], v[142:145], v[198:201], v[58:61]
	v_mfma_f32_16x16x32_bf16 v[46:49], v[134:137], v[214:217], v[46:49]
	v_mfma_f32_16x16x32_bf16 v[42:45], v[142:145], v[214:217], v[42:45]
	v_mfma_f32_16x16x32_bf16 v[30:33], v[134:137], v[222:225], v[30:33]
	v_mfma_f32_16x16x32_bf16 v[26:29], v[142:145], v[222:225], v[26:29]
	v_mfma_f32_16x16x32_bf16 v[14:17], v[134:137], v[230:233], v[14:17]
	v_mfma_f32_16x16x32_bf16 v[10:13], v[142:145], v[230:233], v[10:13]
	s_setprio 0
	s_setprio 1
	v_mfma_f32_16x16x32_bf16 v[54:57], v[172:175], v[194:197], v[54:57]
	v_mfma_f32_16x16x32_bf16 v[50:53], v[186:189], v[194:197], v[50:53]
	v_mfma_f32_16x16x32_bf16 v[38:41], v[172:175], v[210:213], v[38:41]
	v_mfma_f32_16x16x32_bf16 v[34:37], v[186:189], v[210:213], v[34:37]
	v_mfma_f32_16x16x32_bf16 v[22:25], v[172:175], v[218:221], v[22:25]
	v_mfma_f32_16x16x32_bf16 v[18:21], v[186:189], v[218:221], v[18:21]
	v_mfma_f32_16x16x32_bf16 v[6:9], v[172:175], v[226:229], v[6:9]
	v_mfma_f32_16x16x32_bf16 v[2:5], v[186:189], v[226:229], v[2:5]
	v_mfma_f32_16x16x32_bf16 v[54:57], v[176:179], v[198:201], v[54:57]
	v_mfma_f32_16x16x32_bf16 v[50:53], v[190:193], v[198:201], v[50:53]
	v_mfma_f32_16x16x32_bf16 v[38:41], v[176:179], v[214:217], v[38:41]
	v_mfma_f32_16x16x32_bf16 v[34:37], v[190:193], v[214:217], v[34:37]
	v_mfma_f32_16x16x32_bf16 v[22:25], v[176:179], v[222:225], v[22:25]
	v_mfma_f32_16x16x32_bf16 v[18:21], v[190:193], v[222:225], v[18:21]
	v_mfma_f32_16x16x32_bf16 v[6:9], v[176:179], v[230:233], v[6:9]
	v_mfma_f32_16x16x32_bf16 v[2:5], v[190:193], v[230:233], v[2:5]
	s_setprio 0
	s_barrier
	s_add_i32 s45, 0, 0x18000
	v_add_u32_e32 v0, s45, v181
	s_add_i32 s75, 0, 0x1c000
	ds_read_b128 v[130:133], v0
	ds_read_b128 v[134:137], v0 offset:1024
	ds_read_b128 v[138:141], v0 offset:2048
	ds_read_b128 v[142:145], v0 offset:3072
	v_add_u32_e32 v0, s75, v181
	ds_read_b128 v[172:175], v0
	ds_read_b128 v[176:179], v0 offset:1024
	ds_read_b128 v[186:189], v0 offset:2048
	ds_read_b128 v[190:193], v0 offset:3072
	s_add_u32 s34, s34, 0x40000
	s_addc_u32 s35, s35, 0
	s_mov_b32 m0, s48
	v_lshl_add_u64 v[240:241], s[34:35], 0, v[146:147]
	ds_read_b128 v[194:197], v185 offset:32768
	ds_read_b128 v[198:201], v185 offset:33792
	ds_read_b128 v[210:213], v185 offset:34816
	ds_read_b128 v[214:217], v185 offset:35840
	ds_read_b128 v[218:221], v185 offset:36864
	ds_read_b128 v[222:225], v185 offset:37888
	ds_read_b128 v[226:229], v185 offset:38912
	ds_read_b128 v[230:233], v185 offset:39936
	global_load_lds_dwordx4 v[240:241], off
	v_lshl_add_u64 v[240:241], s[34:35], 0, v[150:151]
	s_mov_b32 m0, s49
	s_nop 0
	global_load_lds_dwordx4 v[240:241], off
	s_waitcnt vmcnt(8)
	s_waitcnt lgkmcnt(0)
	s_barrier
	s_setprio 1
	v_mfma_f32_16x16x32_bf16 v[126:129], v[130:133], v[194:197], v[126:129]
	v_mfma_f32_16x16x32_bf16 v[122:125], v[138:141], v[194:197], v[122:125]
	v_mfma_f32_16x16x32_bf16 v[110:113], v[130:133], v[210:213], v[110:113]
	v_mfma_f32_16x16x32_bf16 v[106:109], v[138:141], v[210:213], v[106:109]
	v_mfma_f32_16x16x32_bf16 v[94:97], v[130:133], v[218:221], v[94:97]
	v_mfma_f32_16x16x32_bf16 v[90:93], v[138:141], v[218:221], v[90:93]
	v_mfma_f32_16x16x32_bf16 v[78:81], v[130:133], v[226:229], v[78:81]
	v_mfma_f32_16x16x32_bf16 v[74:77], v[138:141], v[226:229], v[74:77]
	v_mfma_f32_16x16x32_bf16 v[126:129], v[134:137], v[198:201], v[126:129]
	v_mfma_f32_16x16x32_bf16 v[122:125], v[142:145], v[198:201], v[122:125]
	v_mfma_f32_16x16x32_bf16 v[110:113], v[134:137], v[214:217], v[110:113]
	v_mfma_f32_16x16x32_bf16 v[106:109], v[142:145], v[214:217], v[106:109]
	v_mfma_f32_16x16x32_bf16 v[94:97], v[134:137], v[222:225], v[94:97]
	v_mfma_f32_16x16x32_bf16 v[90:93], v[142:145], v[222:225], v[90:93]
	v_mfma_f32_16x16x32_bf16 v[78:81], v[134:137], v[230:233], v[78:81]
	v_mfma_f32_16x16x32_bf16 v[74:77], v[142:145], v[230:233], v[74:77]
	s_setprio 0
	s_setprio 1
	v_mfma_f32_16x16x32_bf16 v[118:121], v[172:175], v[194:197], v[118:121]
	v_mfma_f32_16x16x32_bf16 v[114:117], v[186:189], v[194:197], v[114:117]
	v_mfma_f32_16x16x32_bf16 v[102:105], v[172:175], v[210:213], v[102:105]
	v_mfma_f32_16x16x32_bf16 v[98:101], v[186:189], v[210:213], v[98:101]
	v_mfma_f32_16x16x32_bf16 v[86:89], v[172:175], v[218:221], v[86:89]
	v_mfma_f32_16x16x32_bf16 v[82:85], v[186:189], v[218:221], v[82:85]
	v_mfma_f32_16x16x32_bf16 v[70:73], v[172:175], v[226:229], v[70:73]
	v_mfma_f32_16x16x32_bf16 v[66:69], v[186:189], v[226:229], v[66:69]
	v_mfma_f32_16x16x32_bf16 v[118:121], v[176:179], v[198:201], v[118:121]
	v_mfma_f32_16x16x32_bf16 v[114:117], v[190:193], v[198:201], v[114:117]
	v_mfma_f32_16x16x32_bf16 v[102:105], v[176:179], v[214:217], v[102:105]
	v_mfma_f32_16x16x32_bf16 v[98:101], v[190:193], v[214:217], v[98:101]
	v_mfma_f32_16x16x32_bf16 v[86:89], v[176:179], v[222:225], v[86:89]
	v_mfma_f32_16x16x32_bf16 v[82:85], v[190:193], v[222:225], v[82:85]
	v_mfma_f32_16x16x32_bf16 v[70:73], v[176:179], v[230:233], v[70:73]
	v_mfma_f32_16x16x32_bf16 v[66:69], v[190:193], v[230:233], v[66:69]
	s_setprio 0
	s_barrier
; #define PG8_STAGE(bufoff, gbase, voff) do { _Pragma("unroll") for (int _i = 0; _i < 2; ++_i) \
;         __builtin_amdgcn_global_load_lds((const unsigned*)((const char*)(gbase) + (voff)[_i]), (PG8_LAS unsigned*)(lds + (bufoff) + ldsw + _i * 8192), 16, 0, 0); } while (0)
; #define PG8_LDA(dst, b, h) do { _Pragma("unroll") for (int m = 0; m < 4; ++m) _Pragma("unroll") for (int k = 0; k < 2; ++k) dst[m][k] = *(const PG8_LAS bf16x8*)(lds + PG8_SA(b, h) + aoff + m * 2048 + k * 1024); } while (0)
; #define PG8_BAR __builtin_amdgcn_s_barrier()
; template <class Epi, class Sched, bool ALIGN_EPI = false, bool SP2 = false>
; __device__ __forceinline__ void gemm_phase(PG8_LAS unsigned char* lds, const Gemm g, const Sched& S, const Epi& E, const int wave_s) {
;     ...
;             PG8_LDA(At, 1, 1); PG8_STAGE(PG8_SB(1, 0), b3, voffB); PG8_STAGE(PG8_SB(1, 1), b3 + hstep, voffB); PG8_STAGE(PG8_SA(1, 0), a3, voffA);
;             PG8_WAIT_V(8); PG8_WAIT_L(0); PG8_BAR; PG8_MMA(1, 0, At, B0); PG8_MMA(1, 1, At, B1); PG8_BAR; PG8_SCHED;
;             } else {
;             PG8_LDB(B0, 0, 0); PG8_SCHED; PG8_LDA(At, 0, 0); PG8_STAGE(PG8_SA(1, 1), a1 + hstep, voffA);
;             PG8_WAIT_L(8); PG8_BAR; PG8_WAIT_L(0); PG8_MMA(0, 0, At, B0); PG8_BAR; PG8_SCHED;
;             PG8_LDB(B1, 0, 1); PG8_STAGE(PG8_SB(0, 0), b2, voffB);
;             PG8_BAR; PG8_WAIT_L(0); PG8_MMA(0, 1, At, B1); PG8_BAR;
;             PG8_LDA(At, 0, 1); PG8_STAGE(PG8_SA(0, 0), a2, voffA);
;             PG8_BAR; PG8_WAIT_L(0); PG8_MMA(1, 0, At, B0); PG8_BAR; PG8_SCHED;
;             PG8_STAGE(PG8_SB(0, 1), b2 + hstep, voffB);
;             PG8_WAIT_V(6); PG8_BAR; PG8_MMA(1, 1, At, B1); PG8_BAR;
;             PG8_LDB(B0, 1, 0); PG8_SCHED; PG8_LDA(At, 1, 0); PG8_STAGE(PG8_SA(0, 1), a2 + hstep, voffA);
;             PG8_WAIT_L(8); PG8_BAR; PG8_WAIT_L(0); PG8_MMA(0, 0, At, B0); PG8_BAR; PG8_SCHED;
;             PG8_LDB(B1, 1, 1); PG8_STAGE(PG8_SB(1, 0), b3, voffB);
;             PG8_BAR; PG8_WAIT_L(0); PG8_MMA(0, 1, At, B1); PG8_BAR;
;             PG8_LDA(At, 1, 1); PG8_STAGE(PG8_SA(1, 0), a3, voffA);
;             PG8_BAR; PG8_WAIT_L(0); PG8_MMA(1, 0, At, B0); PG8_BAR; PG8_SCHED;
;             PG8_STAGE(PG8_SB(1, 1), b3 + hstep, voffB);
;             PG8_WAIT_V(6); PG8_BAR; PG8_MMA(1, 1, At, B1); PG8_BAR;
;             }
;         }
;         if constexpr (ALIGN_EPI) { if (wr == 0) PG8_BAR; }
	s_add_i32 s34, s45, s44
	v_lshl_add_u64 v[202:203], v[202:203], 0, s[70:71]
	s_mov_b32 m0, s34
	ds_read_b128 v[194:197], v185 offset:49152
	ds_read_b128 v[198:201], v185 offset:50176
	ds_read_b128 v[210:213], v185 offset:51200
	ds_read_b128 v[214:217], v185 offset:52224
	ds_read_b128 v[218:221], v185 offset:53248
	ds_read_b128 v[222:225], v185 offset:54272
	ds_read_b128 v[226:229], v185 offset:55296
	ds_read_b128 v[230:233], v185 offset:56320
	global_load_lds_dwordx4 v[202:203], off
	s_add_i32 m0, s34, 0x2000
	s_add_u32 s30, s30, 0x40080
	v_lshl_add_u64 v[202:203], v[234:235], 0, s[70:71]
	s_addc_u32 s31, s31, 0
	s_add_i32 s34, s75, s44
	global_load_lds_dwordx4 v[202:203], off
	v_lshl_add_u64 v[202:203], s[30:31], 0, v[148:149]
	s_mov_b32 m0, s34
	s_nop 0
	global_load_lds_dwordx4 v[202:203], off
	v_lshl_add_u64 v[202:203], s[30:31], 0, v[152:153]
	s_add_i32 m0, s34, 0x2000
	s_nop 0
	global_load_lds_dwordx4 v[202:203], off
	v_lshl_add_u64 v[202:203], v[236:237], 0, s[70:71]
	s_mov_b32 m0, s88
	s_nop 0
	global_load_lds_dwordx4 v[202:203], off
	v_lshl_add_u64 v[202:203], v[238:239], 0, s[70:71]
	s_mov_b32 m0, s89
	s_nop 0
	global_load_lds_dwordx4 v[202:203], off
	s_waitcnt vmcnt(8)
	s_waitcnt lgkmcnt(0)
	s_barrier
	s_setprio 1
	v_mfma_f32_16x16x32_bf16 v[62:65], v[130:133], v[194:197], v[62:65]
	v_mfma_f32_16x16x32_bf16 v[58:61], v[138:141], v[194:197], v[58:61]
	v_mfma_f32_16x16x32_bf16 v[46:49], v[130:133], v[210:213], v[46:49]
	v_mfma_f32_16x16x32_bf16 v[42:45], v[138:141], v[210:213], v[42:45]
	v_mfma_f32_16x16x32_bf16 v[30:33], v[130:133], v[218:221], v[30:33]
	v_mfma_f32_16x16x32_bf16 v[26:29], v[138:141], v[218:221], v[26:29]
	v_mfma_f32_16x16x32_bf16 v[14:17], v[130:133], v[226:229], v[14:17]
	v_mfma_f32_16x16x32_bf16 v[10:13], v[138:141], v[226:229], v[10:13]
	v_mfma_f32_16x16x32_bf16 v[62:65], v[134:137], v[198:201], v[62:65]
	v_mfma_f32_16x16x32_bf16 v[58:61], v[142:145], v[198:201], v[58:61]
	v_mfma_f32_16x16x32_bf16 v[46:49], v[134:137], v[214:217], v[46:49]
	v_mfma_f32_16x16x32_bf16 v[42:45], v[142:145], v[214:217], v[42:45]
	v_mfma_f32_16x16x32_bf16 v[30:33], v[134:137], v[222:225], v[30:33]
	v_mfma_f32_16x16x32_bf16 v[26:29], v[142:145], v[222:225], v[26:29]
	v_mfma_f32_16x16x32_bf16 v[14:17], v[134:137], v[230:233], v[14:17]
	v_mfma_f32_16x16x32_bf16 v[10:13], v[142:145], v[230:233], v[10:13]
	s_setprio 0
	s_setprio 1
	v_mfma_f32_16x16x32_bf16 v[54:57], v[172:175], v[194:197], v[54:57]
	v_mfma_f32_16x16x32_bf16 v[50:53], v[186:189], v[194:197], v[50:53]
	v_mfma_f32_16x16x32_bf16 v[38:41], v[172:175], v[210:213], v[38:41]
	v_mfma_f32_16x16x32_bf16 v[34:37], v[186:189], v[210:213], v[34:37]
	v_mfma_f32_16x16x32_bf16 v[22:25], v[172:175], v[218:221], v[22:25]
	v_mfma_f32_16x16x32_bf16 v[18:21], v[186:189], v[218:221], v[18:21]
	v_mfma_f32_16x16x32_bf16 v[6:9], v[172:175], v[226:229], v[6:9]
	v_mfma_f32_16x16x32_bf16 v[2:5], v[186:189], v[226:229], v[2:5]
	v_mfma_f32_16x16x32_bf16 v[54:57], v[176:179], v[198:201], v[54:57]
	v_mfma_f32_16x16x32_bf16 v[50:53], v[190:193], v[198:201], v[50:53]
	v_mfma_f32_16x16x32_bf16 v[38:41], v[176:179], v[214:217], v[38:41]
	v_mfma_f32_16x16x32_bf16 v[34:37], v[190:193], v[214:217], v[34:37]
	v_mfma_f32_16x16x32_bf16 v[22:25], v[176:179], v[222:225], v[22:25]
	v_mfma_f32_16x16x32_bf16 v[18:21], v[190:193], v[222:225], v[18:21]
	v_mfma_f32_16x16x32_bf16 v[6:9], v[176:179], v[230:233], v[6:9]
	v_mfma_f32_16x16x32_bf16 v[2:5], v[190:193], v[230:233], v[2:5]
	s_setprio 0
	s_barrier
	s_add_i32 s68, s68, 2
	s_add_u32 s28, s28, 0x100
	s_addc_u32 s29, s29, 0
	s_add_u32 s64, s64, 0x100
	s_addc_u32 s65, s65, 0
	s_cmp_gt_u32 s68, 13
	s_cbranch_scc0 .LBB0_325
	s_and_b64 vcc, exec, s[14:15]
	s_cbranch_vccz .LBB0_328
	s_barrier

; #define PG8_STAGE(bufoff, gbase, voff) do { _Pragma("unroll") for (int _i = 0; _i < 2; ++_i) \
;         __builtin_amdgcn_global_load_lds((const unsigned*)((const char*)(gbase) + (voff)[_i]), (PG8_LAS unsigned*)(lds + (bufoff) + ldsw + _i * 8192), 16, 0, 0); } while (0)
; #define PG8_LDA(dst, b, h) do { _Pragma("unroll") for (int m = 0; m < 4; ++m) _Pragma("unroll") for (int k = 0; k < 2; ++k) dst[m][k] = *(const PG8_LAS bf16x8*)(lds + PG8_SA(b, h) + aoff + m * 2048 + k * 1024); } while (0)
; #define PG8_LDB(dst, b, h) do { _Pragma("unroll") for (int n = 0; n < 2; ++n) _Pragma("unroll") for (int k = 0; k < 2; ++k) dst[n][k] = *(const PG8_LAS bf16x8*)(lds + PG8_SB(b, h) + boff + n * 2048 + k * 1024); } while (0)
; #define PG8_MMA(ai, bj, At, Bt) do { __builtin_amdgcn_s_setprio(1); _Pragma("unroll") for (int m = 0; m < 4; ++m) _Pragma("unroll") for (int n = 0; n < 2; ++n) _Pragma("unroll") for (int k = 0; k < 2; ++k) \
;         acc[ai][bj][m][n] = __builtin_amdgcn_mfma_f32_16x16x32_bf16(Bt[n][k], At[m][k], acc[ai][bj][m][n], 0, 0, 0); __builtin_amdgcn_s_setprio(0); } while (0)
; #define PG8_WAIT_V(n) asm volatile("s_waitcnt vmcnt(" #n ")" ::: "memory")
; #define PG8_WAIT_L(n) asm volatile("s_waitcnt lgkmcnt(" #n ")" ::: "memory")
; template <class Epi, class Sched, bool ALIGN_EPI = false, bool SP2 = false>
; __device__ __forceinline__ void gemm_phase(PG8_LAS unsigned char* lds, const Gemm g, const Sched& S, const Epi& E, const int wave_s) {
;     ...
;             const bool last = (t == nt - 2);
;             const char* a1 = cA + (size_t)(t + 1) * kstep;
;             const char* a2 = last ? nA : cA + (size_t)(t + 2) * kstep; const char* b2 = last ? nB : cB + (size_t)(t + 2) * kstep;
;             const char* a3 = a2 + kstep; const char* b3 = b2 + kstep;
;             if (last && has_next) S.a_ready(nxt);
;             if constexpr (SP2) {
;             PG8_LDB(B0, 0, 0); PG8_LDB(B1, 0, 1); PG8_SCHED; PG8_LDA(At, 0, 0); PG8_STAGE(PG8_SA(1, 1), a1 + hstep, voffA);
;             PG8_WAIT_V(8); PG8_WAIT_L(0); PG8_BAR; PG8_MMA(0, 0, At, B0); PG8_MMA(0, 1, At, B1); PG8_BAR; PG8_SCHED;
;             PG8_LDA(At, 0, 1); PG8_STAGE(PG8_SB(0, 0), b2, voffB); PG8_STAGE(PG8_SB(0, 1), b2 + hstep, voffB); PG8_STAGE(PG8_SA(0, 0), a2, voffA);
;             PG8_WAIT_V(8); PG8_WAIT_L(0); PG8_BAR; PG8_MMA(1, 0, At, B0); PG8_MMA(1, 1, At, B1); PG8_BAR; PG8_SCHED;
.LBB0_658:
	s_add_u32 s36, s34, 0xfffc0080
	s_addc_u32 s37, s35, -1
	s_add_i32 s45, 0, 0x10000
	s_cmp_eq_u32 s50, 12
	s_cselect_b32 s41, s27, s37
	s_cselect_b32 s40, s55, s36
	v_add_u32_e32 v152, s45, v195
	s_cselect_b32 s37, s25, vcc_hi
	s_cselect_b32 s36, s97, vcc_lo
	s_add_i32 s75, 0, 0x14000
	ds_read_b128 v[94:97], v152
	ds_read_b128 v[98:101], v152 offset:1024
	ds_read_b128 v[148:151], v152 offset:2048
	ds_read_b128 v[162:165], v152 offset:3072
	v_add_u32_e32 v152, s75, v195
	ds_read_b128 v[166:169], v152
	ds_read_b128 v[170:173], v152 offset:1024
	ds_read_b128 v[174:177], v152 offset:2048
	ds_read_b128 v[178:181], v152 offset:3072
	v_lshl_add_u64 v[152:153], s[34:35], 0, v[144:145]
	s_add_i32 m0, s88, 0xc000
	ds_read_b128 v[182:185], v198
	ds_read_b128 v[186:189], v198 offset:1024
	ds_read_b128 v[190:193], v198 offset:2048
	ds_read_b128 v[200:203], v198 offset:3072
	ds_read_b128 v[210:213], v198 offset:4096
	ds_read_b128 v[214:217], v198 offset:5120
	ds_read_b128 v[218:221], v198 offset:6144
	ds_read_b128 v[222:225], v198 offset:7168
	global_load_lds_dwordx4 v[152:153], off
	v_lshl_add_u64 v[152:153], s[34:35], 0, v[146:147]
	s_add_i32 m0, s88, 0xe000
	s_nop 0
	global_load_lds_dwordx4 v[152:153], off
	s_waitcnt vmcnt(8)
	s_waitcnt lgkmcnt(0)
	s_barrier
	s_setprio 1
	v_mfma_f32_16x16x32_bf16 v[134:137], v[94:97], v[182:185], v[134:137]
	v_mfma_f32_16x16x32_bf16 v[130:133], v[148:151], v[182:185], v[130:133]
	v_mfma_f32_16x16x32_bf16 v[126:129], v[94:97], v[190:193], v[126:129]
	v_mfma_f32_16x16x32_bf16 v[122:125], v[148:151], v[190:193], v[122:125]
	v_mfma_f32_16x16x32_bf16 v[118:121], v[94:97], v[210:213], v[118:121]
	v_mfma_f32_16x16x32_bf16 v[114:117], v[148:151], v[210:213], v[114:117]
	v_mfma_f32_16x16x32_bf16 v[110:113], v[94:97], v[218:221], v[110:113]
	v_mfma_f32_16x16x32_bf16 v[106:109], v[148:151], v[218:221], v[106:109]
	v_mfma_f32_16x16x32_bf16 v[134:137], v[98:101], v[186:189], v[134:137]
	v_mfma_f32_16x16x32_bf16 v[130:133], v[162:165], v[186:189], v[130:133]
	v_mfma_f32_16x16x32_bf16 v[126:129], v[98:101], v[200:203], v[126:129]
	v_mfma_f32_16x16x32_bf16 v[122:125], v[162:165], v[200:203], v[122:125]
	v_mfma_f32_16x16x32_bf16 v[118:121], v[98:101], v[214:217], v[118:121]
	v_mfma_f32_16x16x32_bf16 v[114:117], v[162:165], v[214:217], v[114:117]
	v_mfma_f32_16x16x32_bf16 v[110:113], v[98:101], v[222:225], v[110:113]
	v_mfma_f32_16x16x32_bf16 v[106:109], v[162:165], v[222:225], v[106:109]
	s_setprio 0
	s_setprio 1
	v_mfma_f32_16x16x32_bf16 v[58:61], v[166:169], v[182:185], v[58:61]
	v_mfma_f32_16x16x32_bf16 v[62:65], v[174:177], v[182:185], v[62:65]
	v_mfma_f32_16x16x32_bf16 v[54:57], v[166:169], v[190:193], v[54:57]
	v_mfma_f32_16x16x32_bf16 v[50:53], v[174:177], v[190:193], v[50:53]
	v_mfma_f32_16x16x32_bf16 v[46:49], v[166:169], v[210:213], v[46:49]
	v_mfma_f32_16x16x32_bf16 v[42:45], v[174:177], v[210:213], v[42:45]
	v_mfma_f32_16x16x32_bf16 v[38:41], v[166:169], v[218:221], v[38:41]
	v_mfma_f32_16x16x32_bf16 v[34:37], v[174:177], v[218:221], v[34:37]
	v_mfma_f32_16x16x32_bf16 v[58:61], v[170:173], v[186:189], v[58:61]
	v_mfma_f32_16x16x32_bf16 v[62:65], v[178:181], v[186:189], v[62:65]
	v_mfma_f32_16x16x32_bf16 v[54:57], v[170:173], v[200:203], v[54:57]
	v_mfma_f32_16x16x32_bf16 v[50:53], v[178:181], v[200:203], v[50:53]
	v_mfma_f32_16x16x32_bf16 v[46:49], v[170:173], v[214:217], v[46:49]
	v_mfma_f32_16x16x32_bf16 v[42:45], v[178:181], v[214:217], v[42:45]
	v_mfma_f32_16x16x32_bf16 v[38:41], v[170:173], v[222:225], v[38:41]
	v_mfma_f32_16x16x32_bf16 v[34:37], v[178:181], v[222:225], v[34:37]
	s_setprio 0
	s_barrier
	s_add_i32 s45, s45, s68
	v_lshl_add_u64 v[152:153], s[36:37], 0, v[0:1]
	s_mov_b32 m0, s45
	ds_read_b128 v[182:185], v198 offset:16384
	ds_read_b128 v[186:189], v198 offset:17408
	ds_read_b128 v[190:193], v198 offset:18432
	ds_read_b128 v[200:203], v198 offset:19456
	ds_read_b128 v[210:213], v198 offset:20480
	ds_read_b128 v[214:217], v198 offset:21504
	ds_read_b128 v[218:221], v198 offset:22528
	ds_read_b128 v[222:225], v198 offset:23552
	global_load_lds_dwordx4 v[152:153], off
	s_add_i32 m0, s45, 0x2000
	s_add_u32 s80, s36, 0x40000
	v_lshl_add_u64 v[226:227], s[36:37], 0, v[138:139]
	s_addc_u32 s81, s37, 0
	s_add_i32 s45, s75, s68
	global_load_lds_dwordx4 v[226:227], off
	v_lshl_add_u64 v[228:229], s[80:81], 0, v[0:1]
	s_mov_b32 m0, s45
	v_lshl_add_u64 v[230:231], s[40:41], 0, v[140:141]
	global_load_lds_dwordx4 v[228:229], off
	v_lshl_add_u64 v[228:229], s[80:81], 0, v[138:139]
	s_add_i32 m0, s45, 0x2000
	s_nop 0
	global_load_lds_dwordx4 v[228:229], off
	v_lshl_add_u64 v[228:229], s[40:41], 0, v[142:143]
	s_mov_b32 m0, s88
	s_nop 0
	global_load_lds_dwordx4 v[228:229], off
	s_mov_b32 m0, s89
	s_nop 0
	global_load_lds_dwordx4 v[230:231], off
	s_waitcnt vmcnt(8)
	s_waitcnt lgkmcnt(0)
	s_barrier
; #define PG8_STAGE(bufoff, gbase, voff) do { _Pragma("unroll") for (int _i = 0; _i < 2; ++_i) \
;         __builtin_amdgcn_global_load_lds((const unsigned*)((const char*)(gbase) + (voff)[_i]), (PG8_LAS unsigned*)(lds + (bufoff) + ldsw + _i * 8192), 16, 0, 0); } while (0)
; #define PG8_LDA(dst, b, h) do { _Pragma("unroll") for (int m = 0; m < 4; ++m) _Pragma("unroll") for (int k = 0; k < 2; ++k) dst[m][k] = *(const PG8_LAS bf16x8*)(lds + PG8_SA(b, h) + aoff + m * 2048 + k * 1024); } while (0)
; #define PG8_LDB(dst, b, h) do { _Pragma("unroll") for (int n = 0; n < 2; ++n) _Pragma("unroll") for (int k = 0; k < 2; ++k) dst[n][k] = *(const PG8_LAS bf16x8*)(lds + PG8_SB(b, h) + boff + n * 2048 + k * 1024); } while (0)
; #define PG8_MMA(ai, bj, At, Bt) do { __builtin_amdgcn_s_setprio(1); _Pragma("unroll") for (int m = 0; m < 4; ++m) _Pragma("unroll") for (int n = 0; n < 2; ++n) _Pragma("unroll") for (int k = 0; k < 2; ++k) \
;         acc[ai][bj][m][n] = __builtin_amdgcn_mfma_f32_16x16x32_bf16(Bt[n][k], At[m][k], acc[ai][bj][m][n], 0, 0, 0); __builtin_amdgcn_s_setprio(0); } while (0)
; #define PG8_WAIT_V(n) asm volatile("s_waitcnt vmcnt(" #n ")" ::: "memory")
; #define PG8_WAIT_L(n) asm volatile("s_waitcnt lgkmcnt(" #n ")" ::: "memory")
; #define PG8_BAR __builtin_amdgcn_s_barrier()
; #define PG8_SCHED __builtin_amdgcn_sched_barrier(0)
; template <class Epi, class Sched, bool ALIGN_EPI = false, bool SP2 = false>
; __device__ __forceinline__ void gemm_phase(PG8_LAS unsigned char* lds, const Gemm g, const Sched& S, const Epi& E, const int wave_s) {
;     ...
;             PG8_WAIT_V(8); PG8_WAIT_L(0); PG8_BAR; PG8_MMA(1, 0, At, B0); PG8_MMA(1, 1, At, B1); PG8_BAR; PG8_SCHED;
;             PG8_LDB(B0, 1, 0); PG8_LDB(B1, 1, 1); PG8_SCHED; PG8_LDA(At, 1, 0); PG8_STAGE(PG8_SA(0, 1), a2 + hstep, voffA);
;             PG8_WAIT_V(8); PG8_WAIT_L(0); PG8_BAR; PG8_MMA(0, 0, At, B0); PG8_MMA(0, 1, At, B1); PG8_BAR; PG8_SCHED;
	s_setprio 1
	v_mfma_f32_16x16x32_bf16 v[102:105], v[94:97], v[182:185], v[102:105]
	v_mfma_f32_16x16x32_bf16 v[90:93], v[148:151], v[182:185], v[90:93]
	v_mfma_f32_16x16x32_bf16 v[86:89], v[94:97], v[190:193], v[86:89]
	v_mfma_f32_16x16x32_bf16 v[82:85], v[148:151], v[190:193], v[82:85]
	v_mfma_f32_16x16x32_bf16 v[78:81], v[94:97], v[210:213], v[78:81]
	v_mfma_f32_16x16x32_bf16 v[74:77], v[148:151], v[210:213], v[74:77]
	v_mfma_f32_16x16x32_bf16 v[70:73], v[94:97], v[218:221], v[70:73]
	v_mfma_f32_16x16x32_bf16 v[66:69], v[148:151], v[218:221], v[66:69]
	v_mfma_f32_16x16x32_bf16 v[102:105], v[98:101], v[186:189], v[102:105]
	v_mfma_f32_16x16x32_bf16 v[90:93], v[162:165], v[186:189], v[90:93]
	v_mfma_f32_16x16x32_bf16 v[86:89], v[98:101], v[200:203], v[86:89]
	v_mfma_f32_16x16x32_bf16 v[82:85], v[162:165], v[200:203], v[82:85]
	v_mfma_f32_16x16x32_bf16 v[78:81], v[98:101], v[214:217], v[78:81]
	v_mfma_f32_16x16x32_bf16 v[74:77], v[162:165], v[214:217], v[74:77]
	v_mfma_f32_16x16x32_bf16 v[70:73], v[98:101], v[222:225], v[70:73]
	v_mfma_f32_16x16x32_bf16 v[66:69], v[162:165], v[222:225], v[66:69]
	s_setprio 0
	s_setprio 1
	v_mfma_f32_16x16x32_bf16 v[30:33], v[166:169], v[182:185], v[30:33]
	v_mfma_f32_16x16x32_bf16 v[26:29], v[174:177], v[182:185], v[26:29]
	v_mfma_f32_16x16x32_bf16 v[22:25], v[166:169], v[190:193], v[22:25]
	v_mfma_f32_16x16x32_bf16 v[18:21], v[174:177], v[190:193], v[18:21]
	v_mfma_f32_16x16x32_bf16 v[14:17], v[166:169], v[210:213], v[14:17]
	v_mfma_f32_16x16x32_bf16 v[10:13], v[174:177], v[210:213], v[10:13]
	v_mfma_f32_16x16x32_bf16 v[6:9], v[166:169], v[218:221], v[6:9]
	v_mfma_f32_16x16x32_bf16 v[2:5], v[174:177], v[218:221], v[2:5]
	v_mfma_f32_16x16x32_bf16 v[30:33], v[170:173], v[186:189], v[30:33]
	v_mfma_f32_16x16x32_bf16 v[26:29], v[178:181], v[186:189], v[26:29]
	v_mfma_f32_16x16x32_bf16 v[22:25], v[170:173], v[200:203], v[22:25]
	v_mfma_f32_16x16x32_bf16 v[18:21], v[178:181], v[200:203], v[18:21]
	v_mfma_f32_16x16x32_bf16 v[14:17], v[170:173], v[214:217], v[14:17]
	v_mfma_f32_16x16x32_bf16 v[10:13], v[178:181], v[214:217], v[10:13]
	v_mfma_f32_16x16x32_bf16 v[6:9], v[170:173], v[222:225], v[6:9]
	v_mfma_f32_16x16x32_bf16 v[2:5], v[178:181], v[222:225], v[2:5]
	s_setprio 0
	s_barrier
	s_add_i32 s45, 0, 0x18000
	s_add_i32 s75, 0, 0x1c000
	v_add_u32_e32 v162, s45, v195
	v_add_u32_e32 v178, s75, v195
	ds_read_b128 v[94:97], v162
	ds_read_b128 v[98:101], v162 offset:1024
	ds_read_b128 v[148:151], v162 offset:2048
	ds_read_b128 v[162:165], v162 offset:3072
	ds_read_b128 v[166:169], v178
	ds_read_b128 v[170:173], v178 offset:1024
	ds_read_b128 v[174:177], v178 offset:2048
	ds_read_b128 v[178:181], v178 offset:3072
	s_add_u32 s40, s40, 0x40000
	s_addc_u32 s41, s41, 0
	s_mov_b32 m0, s38
	v_lshl_add_u64 v[232:233], s[40:41], 0, v[142:143]
	ds_read_b128 v[182:185], v198 offset:32768
	ds_read_b128 v[186:189], v198 offset:33792
	ds_read_b128 v[190:193], v198 offset:34816
	ds_read_b128 v[200:203], v198 offset:35840
	ds_read_b128 v[210:213], v198 offset:36864
	ds_read_b128 v[214:217], v198 offset:37888
	ds_read_b128 v[218:221], v198 offset:38912
	ds_read_b128 v[222:225], v198 offset:39936
	global_load_lds_dwordx4 v[232:233], off
	v_lshl_add_u64 v[232:233], s[40:41], 0, v[140:141]
	s_mov_b32 m0, s39
	s_nop 0
	global_load_lds_dwordx4 v[232:233], off
	s_waitcnt vmcnt(8)
	s_waitcnt lgkmcnt(0)
	s_barrier
	s_setprio 1
	v_mfma_f32_16x16x32_bf16 v[134:137], v[94:97], v[182:185], v[134:137]
	v_mfma_f32_16x16x32_bf16 v[130:133], v[148:151], v[182:185], v[130:133]
	v_mfma_f32_16x16x32_bf16 v[126:129], v[94:97], v[190:193], v[126:129]
	v_mfma_f32_16x16x32_bf16 v[122:125], v[148:151], v[190:193], v[122:125]
	v_mfma_f32_16x16x32_bf16 v[118:121], v[94:97], v[210:213], v[118:121]
	v_mfma_f32_16x16x32_bf16 v[114:117], v[148:151], v[210:213], v[114:117]
	v_mfma_f32_16x16x32_bf16 v[110:113], v[94:97], v[218:221], v[110:113]
	v_mfma_f32_16x16x32_bf16 v[106:109], v[148:151], v[218:221], v[106:109]
	v_mfma_f32_16x16x32_bf16 v[134:137], v[98:101], v[186:189], v[134:137]
	v_mfma_f32_16x16x32_bf16 v[130:133], v[162:165], v[186:189], v[130:133]
	v_mfma_f32_16x16x32_bf16 v[126:129], v[98:101], v[200:203], v[126:129]
	v_mfma_f32_16x16x32_bf16 v[122:125], v[162:165], v[200:203], v[122:125]
	v_mfma_f32_16x16x32_bf16 v[118:121], v[98:101], v[214:217], v[118:121]
	v_mfma_f32_16x16x32_bf16 v[114:117], v[162:165], v[214:217], v[114:117]
	v_mfma_f32_16x16x32_bf16 v[110:113], v[98:101], v[222:225], v[110:113]
	v_mfma_f32_16x16x32_bf16 v[106:109], v[162:165], v[222:225], v[106:109]
	s_setprio 0
	s_setprio 1
	v_mfma_f32_16x16x32_bf16 v[58:61], v[166:169], v[182:185], v[58:61]
	v_mfma_f32_16x16x32_bf16 v[62:65], v[174:177], v[182:185], v[62:65]
	v_mfma_f32_16x16x32_bf16 v[54:57], v[166:169], v[190:193], v[54:57]
	v_mfma_f32_16x16x32_bf16 v[50:53], v[174:177], v[190:193], v[50:53]
	v_mfma_f32_16x16x32_bf16 v[46:49], v[166:169], v[210:213], v[46:49]
	v_mfma_f32_16x16x32_bf16 v[42:45], v[174:177], v[210:213], v[42:45]
	v_mfma_f32_16x16x32_bf16 v[38:41], v[166:169], v[218:221], v[38:41]
	v_mfma_f32_16x16x32_bf16 v[34:37], v[174:177], v[218:221], v[34:37]
	v_mfma_f32_16x16x32_bf16 v[58:61], v[170:173], v[186:189], v[58:61]
	v_mfma_f32_16x16x32_bf16 v[62:65], v[178:181], v[186:189], v[62:65]
	v_mfma_f32_16x16x32_bf16 v[54:57], v[170:173], v[200:203], v[54:57]
	v_mfma_f32_16x16x32_bf16 v[50:53], v[178:181], v[200:203], v[50:53]
	v_mfma_f32_16x16x32_bf16 v[46:49], v[170:173], v[214:217], v[46:49]
	v_mfma_f32_16x16x32_bf16 v[42:45], v[178:181], v[214:217], v[42:45]
	v_mfma_f32_16x16x32_bf16 v[38:41], v[170:173], v[222:225], v[38:41]
	v_mfma_f32_16x16x32_bf16 v[34:37], v[178:181], v[222:225], v[34:37]
	s_setprio 0
	s_barrier
; #define PG8_STAGE(bufoff, gbase, voff) do { _Pragma("unroll") for (int _i = 0; _i < 2; ++_i) \
;         __builtin_amdgcn_global_load_lds((const unsigned*)((const char*)(gbase) + (voff)[_i]), (PG8_LAS unsigned*)(lds + (bufoff) + ldsw + _i * 8192), 16, 0, 0); } while (0)
; #define PG8_LDA(dst, b, h) do { _Pragma("unroll") for (int m = 0; m < 4; ++m) _Pragma("unroll") for (int k = 0; k < 2; ++k) dst[m][k] = *(const PG8_LAS bf16x8*)(lds + PG8_SA(b, h) + aoff + m * 2048 + k * 1024); } while (0)
; #define PG8_BAR __builtin_amdgcn_s_barrier()
; template <class Epi, class Sched, bool ALIGN_EPI = false, bool SP2 = false>
; __device__ __forceinline__ void gemm_phase(PG8_LAS unsigned char* lds, const Gemm g, const Sched& S, const Epi& E, const int wave_s) {
;     ...
;             PG8_LDA(At, 1, 1); PG8_STAGE(PG8_SB(1, 0), b3, voffB); PG8_STAGE(PG8_SB(1, 1), b3 + hstep, voffB); PG8_STAGE(PG8_SA(1, 0), a3, voffA);
;             PG8_WAIT_V(8); PG8_WAIT_L(0); PG8_BAR; PG8_MMA(1, 0, At, B0); PG8_MMA(1, 1, At, B1); PG8_BAR; PG8_SCHED;
;             } else {
;             PG8_LDB(B0, 0, 0); PG8_SCHED; PG8_LDA(At, 0, 0); PG8_STAGE(PG8_SA(1, 1), a1 + hstep, voffA);
;             PG8_WAIT_L(8); PG8_BAR; PG8_WAIT_L(0); PG8_MMA(0, 0, At, B0); PG8_BAR; PG8_SCHED;
;             PG8_LDB(B1, 0, 1); PG8_STAGE(PG8_SB(0, 0), b2, voffB);
;             PG8_BAR; PG8_WAIT_L(0); PG8_MMA(0, 1, At, B1); PG8_BAR;
;             PG8_LDA(At, 0, 1); PG8_STAGE(PG8_SA(0, 0), a2, voffA);
;             PG8_BAR; PG8_WAIT_L(0); PG8_MMA(1, 0, At, B0); PG8_BAR; PG8_SCHED;
;             PG8_STAGE(PG8_SB(0, 1), b2 + hstep, voffB);
;             PG8_WAIT_V(6); PG8_BAR; PG8_MMA(1, 1, At, B1); PG8_BAR;
;             PG8_LDB(B0, 1, 0); PG8_SCHED; PG8_LDA(At, 1, 0); PG8_STAGE(PG8_SA(0, 1), a2 + hstep, voffA);
;             PG8_WAIT_L(8); PG8_BAR; PG8_WAIT_L(0); PG8_MMA(0, 0, At, B0); PG8_BAR; PG8_SCHED;
;             PG8_LDB(B1, 1, 1); PG8_STAGE(PG8_SB(1, 0), b3, voffB);
;             PG8_BAR; PG8_WAIT_L(0); PG8_MMA(0, 1, At, B1); PG8_BAR;
;             PG8_LDA(At, 1, 1); PG8_STAGE(PG8_SA(1, 0), a3, voffA);
;             PG8_BAR; PG8_WAIT_L(0); PG8_MMA(1, 0, At, B0); PG8_BAR; PG8_SCHED;
;             PG8_STAGE(PG8_SB(1, 1), b3 + hstep, voffB);
;             PG8_WAIT_V(6); PG8_BAR; PG8_MMA(1, 1, At, B1); PG8_BAR;
;             }
;         }
;         if constexpr (ALIGN_EPI) { if (wr == 0) PG8_BAR; }
	s_add_i32 s40, s45, s68
	v_lshl_add_u64 v[152:153], v[152:153], 0, s[70:71]
	s_mov_b32 m0, s40
	ds_read_b128 v[182:185], v198 offset:49152
	ds_read_b128 v[186:189], v198 offset:50176
	ds_read_b128 v[190:193], v198 offset:51200
	ds_read_b128 v[200:203], v198 offset:52224
	ds_read_b128 v[210:213], v198 offset:53248
	ds_read_b128 v[214:217], v198 offset:54272
	ds_read_b128 v[218:221], v198 offset:55296
	ds_read_b128 v[222:225], v198 offset:56320
	global_load_lds_dwordx4 v[152:153], off
	s_add_i32 m0, s40, 0x2000
	s_add_u32 s36, s36, 0x40080
	v_lshl_add_u64 v[152:153], v[226:227], 0, s[70:71]
	s_addc_u32 s37, s37, 0
	s_add_i32 s40, s75, s68
	global_load_lds_dwordx4 v[152:153], off
	v_lshl_add_u64 v[152:153], s[36:37], 0, v[0:1]
	s_mov_b32 m0, s40
	s_nop 0
	global_load_lds_dwordx4 v[152:153], off
	v_lshl_add_u64 v[152:153], s[36:37], 0, v[138:139]
	s_add_i32 m0, s40, 0x2000
	s_nop 0
	global_load_lds_dwordx4 v[152:153], off
	v_lshl_add_u64 v[152:153], v[228:229], 0, s[70:71]
	s_mov_b32 m0, s44
	s_nop 0
	global_load_lds_dwordx4 v[152:153], off
	v_lshl_add_u64 v[152:153], v[230:231], 0, s[70:71]
	s_mov_b32 m0, s54
	s_nop 0
	global_load_lds_dwordx4 v[152:153], off
	s_waitcnt vmcnt(8)
	s_waitcnt lgkmcnt(0)
	s_barrier
	s_setprio 1
	v_mfma_f32_16x16x32_bf16 v[102:105], v[94:97], v[182:185], v[102:105]
	v_mfma_f32_16x16x32_bf16 v[90:93], v[148:151], v[182:185], v[90:93]
	v_mfma_f32_16x16x32_bf16 v[86:89], v[94:97], v[190:193], v[86:89]
	v_mfma_f32_16x16x32_bf16 v[82:85], v[148:151], v[190:193], v[82:85]
	v_mfma_f32_16x16x32_bf16 v[78:81], v[94:97], v[210:213], v[78:81]
	v_mfma_f32_16x16x32_bf16 v[74:77], v[148:151], v[210:213], v[74:77]
	v_mfma_f32_16x16x32_bf16 v[70:73], v[94:97], v[218:221], v[70:73]
	v_mfma_f32_16x16x32_bf16 v[66:69], v[148:151], v[218:221], v[66:69]
	v_mfma_f32_16x16x32_bf16 v[102:105], v[98:101], v[186:189], v[102:105]
	v_mfma_f32_16x16x32_bf16 v[90:93], v[162:165], v[186:189], v[90:93]
	v_mfma_f32_16x16x32_bf16 v[86:89], v[98:101], v[200:203], v[86:89]
	v_mfma_f32_16x16x32_bf16 v[82:85], v[162:165], v[200:203], v[82:85]
	v_mfma_f32_16x16x32_bf16 v[78:81], v[98:101], v[214:217], v[78:81]
	v_mfma_f32_16x16x32_bf16 v[74:77], v[162:165], v[214:217], v[74:77]
	v_mfma_f32_16x16x32_bf16 v[70:73], v[98:101], v[222:225], v[70:73]
	v_mfma_f32_16x16x32_bf16 v[66:69], v[162:165], v[222:225], v[66:69]
	s_setprio 0
	s_setprio 1
	v_mfma_f32_16x16x32_bf16 v[30:33], v[166:169], v[182:185], v[30:33]
	v_mfma_f32_16x16x32_bf16 v[26:29], v[174:177], v[182:185], v[26:29]
	v_mfma_f32_16x16x32_bf16 v[22:25], v[166:169], v[190:193], v[22:25]
	v_mfma_f32_16x16x32_bf16 v[18:21], v[174:177], v[190:193], v[18:21]
	v_mfma_f32_16x16x32_bf16 v[14:17], v[166:169], v[210:213], v[14:17]
	v_mfma_f32_16x16x32_bf16 v[10:13], v[174:177], v[210:213], v[10:13]
	v_mfma_f32_16x16x32_bf16 v[6:9], v[166:169], v[218:221], v[6:9]
	v_mfma_f32_16x16x32_bf16 v[2:5], v[174:177], v[218:221], v[2:5]
	v_mfma_f32_16x16x32_bf16 v[30:33], v[170:173], v[186:189], v[30:33]
	v_mfma_f32_16x16x32_bf16 v[26:29], v[178:181], v[186:189], v[26:29]
	v_mfma_f32_16x16x32_bf16 v[22:25], v[170:173], v[200:203], v[22:25]
	v_mfma_f32_16x16x32_bf16 v[18:21], v[178:181], v[200:203], v[18:21]
	v_mfma_f32_16x16x32_bf16 v[14:17], v[170:173], v[214:217], v[14:17]
	v_mfma_f32_16x16x32_bf16 v[10:13], v[178:181], v[214:217], v[10:13]
	v_mfma_f32_16x16x32_bf16 v[6:9], v[170:173], v[222:225], v[6:9]
	v_mfma_f32_16x16x32_bf16 v[2:5], v[178:181], v[222:225], v[2:5]
	s_setprio 0
	s_barrier
	s_add_i32 s50, s50, 2
	s_add_u32 s34, s34, 0x100
	s_addc_u32 s35, s35, 0
	s_add_u32 vcc_lo, vcc_lo, 0x100
	s_addc_u32 vcc_hi, vcc_hi, 0
	s_cmp_gt_u32 s50, 13
	s_cbranch_scc0 .LBB0_658
	s_and_b64 vcc, exec, s[22:23]
	s_cbranch_vccz .LBB0_661
	s_barrier

; #define PG8_STAGE(bufoff, gbase, voff) do { _Pragma("unroll") for (int _i = 0; _i < 2; ++_i) \
;         __builtin_amdgcn_global_load_lds((const unsigned*)((const char*)(gbase) + (voff)[_i]), (PG8_LAS unsigned*)(lds + (bufoff) + ldsw + _i * 8192), 16, 0, 0); } while (0)
; #define PG8_LDA(dst, b, h) do { _Pragma("unroll") for (int m = 0; m < 4; ++m) _Pragma("unroll") for (int k = 0; k < 2; ++k) dst[m][k] = *(const PG8_LAS bf16x8*)(lds + PG8_SA(b, h) + aoff + m * 2048 + k * 1024); } while (0)
; #define PG8_LDB(dst, b, h) do { _Pragma("unroll") for (int n = 0; n < 2; ++n) _Pragma("unroll") for (int k = 0; k < 2; ++k) dst[n][k] = *(const PG8_LAS bf16x8*)(lds + PG8_SB(b, h) + boff + n * 2048 + k * 1024); } while (0)
; #define PG8_MMA(ai, bj, At, Bt) do { __builtin_amdgcn_s_setprio(1); _Pragma("unroll") for (int m = 0; m < 4; ++m) _Pragma("unroll") for (int n = 0; n < 2; ++n) _Pragma("unroll") for (int k = 0; k < 2; ++k) \
;         acc[ai][bj][m][n] = __builtin_amdgcn_mfma_f32_16x16x32_bf16(Bt[n][k], At[m][k], acc[ai][bj][m][n], 0, 0, 0); __builtin_amdgcn_s_setprio(0); } while (0)
; #define PG8_WAIT_V(n) asm volatile("s_waitcnt vmcnt(" #n ")" ::: "memory")
; #define PG8_WAIT_L(n) asm volatile("s_waitcnt lgkmcnt(" #n ")" ::: "memory")
; template <class Epi, class Sched, bool ALIGN_EPI = false, bool SP2 = false>
; __device__ __forceinline__ void gemm_phase(PG8_LAS unsigned char* lds, const Gemm g, const Sched& S, const Epi& E, const int wave_s) {
;     ...
;             const bool last = (t == nt - 2);
;             const char* a1 = cA + (size_t)(t + 1) * kstep;
;             const char* a2 = last ? nA : cA + (size_t)(t + 2) * kstep; const char* b2 = last ? nB : cB + (size_t)(t + 2) * kstep;
;             const char* a3 = a2 + kstep; const char* b3 = b2 + kstep;
;             if (last && has_next) S.a_ready(nxt);
;             if constexpr (SP2) {
;             PG8_LDB(B0, 0, 0); PG8_LDB(B1, 0, 1); PG8_SCHED; PG8_LDA(At, 0, 0); PG8_STAGE(PG8_SA(1, 1), a1 + hstep, voffA);
;             PG8_WAIT_V(8); PG8_WAIT_L(0); PG8_BAR; PG8_MMA(0, 0, At, B0); PG8_MMA(0, 1, At, B1); PG8_BAR; PG8_SCHED;
;             PG8_LDA(At, 0, 1); PG8_STAGE(PG8_SB(0, 0), b2, voffB); PG8_STAGE(PG8_SB(0, 1), b2 + hstep, voffB); PG8_STAGE(PG8_SA(0, 0), a2, voffA);
;             PG8_WAIT_V(8); PG8_WAIT_L(0); PG8_BAR; PG8_MMA(1, 0, At, B0); PG8_MMA(1, 1, At, B1); PG8_BAR; PG8_SCHED;
.LBB0_734:
	s_add_u32 s26, s24, 0xfffc0080
	s_addc_u32 s27, s25, -1
	s_add_i32 s45, 0, 0x10000
	s_cmp_eq_u32 s50, 12
	s_cselect_b32 s29, s19, s27
	s_cselect_b32 s28, s54, s26
	s_cselect_b32 s27, s17, s59
	s_cselect_b32 s26, s55, s58
	s_add_i32 s68, 0, 0x14000
	v_add_u32_e32 v50, s45, v171
	v_add_u32_e32 v152, s68, v171
	ds_read_b128 v[26:29], v50
	ds_read_b128 v[30:33], v50 offset:1024
	ds_read_b128 v[46:49], v50 offset:2048
	ds_read_b128 v[50:53], v50 offset:3072
	ds_read_b128 v[162:165], v152
	ds_read_b128 v[166:169], v152 offset:1024
	ds_read_b128 v[176:179], v152 offset:2048
	ds_read_b128 v[180:183], v152 offset:3072
	v_lshl_add_u64 v[152:153], s[24:25], 0, v[148:149]
	s_add_i32 m0, s35, 0xc000
	ds_read_b128 v[184:187], v174
	ds_read_b128 v[188:191], v174 offset:1024
	ds_read_b128 v[192:195], v174 offset:2048
	ds_read_b128 v[196:199], v174 offset:3072
	ds_read_b128 v[200:203], v174 offset:4096
	ds_read_b128 v[210:213], v174 offset:5120
	ds_read_b128 v[214:217], v174 offset:6144
	ds_read_b128 v[218:221], v174 offset:7168
	global_load_lds_dwordx4 v[152:153], off
	v_lshl_add_u64 v[152:153], s[24:25], 0, v[150:151]
	s_add_i32 m0, s35, 0xe000
	s_nop 0
	global_load_lds_dwordx4 v[152:153], off
	s_waitcnt vmcnt(8)
	s_waitcnt lgkmcnt(0)
	s_barrier
	s_setprio 1
	v_mfma_f32_16x16x32_bf16 v[142:145], v[26:29], v[184:187], v[142:145]
	v_mfma_f32_16x16x32_bf16 v[138:141], v[46:49], v[184:187], v[138:141]
	v_mfma_f32_16x16x32_bf16 v[126:129], v[26:29], v[192:195], v[126:129]
	v_mfma_f32_16x16x32_bf16 v[122:125], v[46:49], v[192:195], v[122:125]
	v_mfma_f32_16x16x32_bf16 v[110:113], v[26:29], v[200:203], v[110:113]
	v_mfma_f32_16x16x32_bf16 v[106:109], v[46:49], v[200:203], v[106:109]
	v_mfma_f32_16x16x32_bf16 v[94:97], v[26:29], v[214:217], v[94:97]
	v_mfma_f32_16x16x32_bf16 v[90:93], v[46:49], v[214:217], v[90:93]
	v_mfma_f32_16x16x32_bf16 v[142:145], v[30:33], v[188:191], v[142:145]
	v_mfma_f32_16x16x32_bf16 v[138:141], v[50:53], v[188:191], v[138:141]
	v_mfma_f32_16x16x32_bf16 v[126:129], v[30:33], v[196:199], v[126:129]
	v_mfma_f32_16x16x32_bf16 v[122:125], v[50:53], v[196:199], v[122:125]
	v_mfma_f32_16x16x32_bf16 v[110:113], v[30:33], v[210:213], v[110:113]
	v_mfma_f32_16x16x32_bf16 v[106:109], v[50:53], v[210:213], v[106:109]
	v_mfma_f32_16x16x32_bf16 v[94:97], v[30:33], v[218:221], v[94:97]
	v_mfma_f32_16x16x32_bf16 v[90:93], v[50:53], v[218:221], v[90:93]
	s_setprio 0
	s_setprio 1
	v_mfma_f32_16x16x32_bf16 v[134:137], v[162:165], v[184:187], v[134:137]
	v_mfma_f32_16x16x32_bf16 v[130:133], v[176:179], v[184:187], v[130:133]
	v_mfma_f32_16x16x32_bf16 v[118:121], v[162:165], v[192:195], v[118:121]
	v_mfma_f32_16x16x32_bf16 v[114:117], v[176:179], v[192:195], v[114:117]
	v_mfma_f32_16x16x32_bf16 v[102:105], v[162:165], v[200:203], v[102:105]
	v_mfma_f32_16x16x32_bf16 v[98:101], v[176:179], v[200:203], v[98:101]
	v_mfma_f32_16x16x32_bf16 v[86:89], v[162:165], v[214:217], v[86:89]
	v_mfma_f32_16x16x32_bf16 v[82:85], v[176:179], v[214:217], v[82:85]
	v_mfma_f32_16x16x32_bf16 v[134:137], v[166:169], v[188:191], v[134:137]
	v_mfma_f32_16x16x32_bf16 v[130:133], v[180:183], v[188:191], v[130:133]
	v_mfma_f32_16x16x32_bf16 v[118:121], v[166:169], v[196:199], v[118:121]
	v_mfma_f32_16x16x32_bf16 v[114:117], v[180:183], v[196:199], v[114:117]
	v_mfma_f32_16x16x32_bf16 v[102:105], v[166:169], v[210:213], v[102:105]
	v_mfma_f32_16x16x32_bf16 v[98:101], v[180:183], v[210:213], v[98:101]
	v_mfma_f32_16x16x32_bf16 v[86:89], v[166:169], v[218:221], v[86:89]
	v_mfma_f32_16x16x32_bf16 v[82:85], v[180:183], v[218:221], v[82:85]
	s_setprio 0
	s_barrier
	s_add_i32 s45, s45, s34
	v_lshl_add_u64 v[152:153], s[26:27], 0, v[0:1]
	s_mov_b32 m0, s45
	ds_read_b128 v[184:187], v174 offset:16384
	ds_read_b128 v[188:191], v174 offset:17408
	ds_read_b128 v[192:195], v174 offset:18432
	ds_read_b128 v[196:199], v174 offset:19456
	ds_read_b128 v[200:203], v174 offset:20480
	ds_read_b128 v[210:213], v174 offset:21504
	ds_read_b128 v[214:217], v174 offset:22528
	ds_read_b128 v[218:221], v174 offset:23552
	global_load_lds_dwordx4 v[152:153], off
	s_add_i32 m0, s45, 0x2000
	s_add_u32 s64, s26, 0x40000
	v_lshl_add_u64 v[222:223], s[26:27], 0, v[146:147]
	s_addc_u32 s65, s27, 0
	s_add_i32 s45, s68, s34
	global_load_lds_dwordx4 v[222:223], off
	v_lshl_add_u64 v[224:225], s[64:65], 0, v[0:1]
	s_mov_b32 m0, s45
	v_lshl_add_u64 v[226:227], s[28:29], 0, v[146:147]
	global_load_lds_dwordx4 v[224:225], off
	v_lshl_add_u64 v[224:225], s[64:65], 0, v[146:147]
	s_add_i32 m0, s45, 0x2000
	s_nop 0
	global_load_lds_dwordx4 v[224:225], off
	v_lshl_add_u64 v[224:225], s[28:29], 0, v[0:1]
	s_mov_b32 m0, s35
	s_nop 0
	global_load_lds_dwordx4 v[224:225], off
	s_mov_b32 m0, s36
	s_nop 0
	global_load_lds_dwordx4 v[226:227], off
	s_waitcnt vmcnt(8)
	s_waitcnt lgkmcnt(0)
	s_barrier
; #define PG8_STAGE(bufoff, gbase, voff) do { _Pragma("unroll") for (int _i = 0; _i < 2; ++_i) \
;         __builtin_amdgcn_global_load_lds((const unsigned*)((const char*)(gbase) + (voff)[_i]), (PG8_LAS unsigned*)(lds + (bufoff) + ldsw + _i * 8192), 16, 0, 0); } while (0)
; #define PG8_LDA(dst, b, h) do { _Pragma("unroll") for (int m = 0; m < 4; ++m) _Pragma("unroll") for (int k = 0; k < 2; ++k) dst[m][k] = *(const PG8_LAS bf16x8*)(lds + PG8_SA(b, h) + aoff + m * 2048 + k * 1024); } while (0)
; #define PG8_LDB(dst, b, h) do { _Pragma("unroll") for (int n = 0; n < 2; ++n) _Pragma("unroll") for (int k = 0; k < 2; ++k) dst[n][k] = *(const PG8_LAS bf16x8*)(lds + PG8_SB(b, h) + boff + n * 2048 + k * 1024); } while (0)
; #define PG8_MMA(ai, bj, At, Bt) do { __builtin_amdgcn_s_setprio(1); _Pragma("unroll") for (int m = 0; m < 4; ++m) _Pragma("unroll") for (int n = 0; n < 2; ++n) _Pragma("unroll") for (int k = 0; k < 2; ++k) \
;         acc[ai][bj][m][n] = __builtin_amdgcn_mfma_f32_16x16x32_bf16(Bt[n][k], At[m][k], acc[ai][bj][m][n], 0, 0, 0); __builtin_amdgcn_s_setprio(0); } while (0)
; #define PG8_WAIT_V(n) asm volatile("s_waitcnt vmcnt(" #n ")" ::: "memory")
; #define PG8_WAIT_L(n) asm volatile("s_waitcnt lgkmcnt(" #n ")" ::: "memory")
; #define PG8_BAR __builtin_amdgcn_s_barrier()
; #define PG8_SCHED __builtin_amdgcn_sched_barrier(0)
; template <class Epi, class Sched, bool ALIGN_EPI = false, bool SP2 = false>
; __device__ __forceinline__ void gemm_phase(PG8_LAS unsigned char* lds, const Gemm g, const Sched& S, const Epi& E, const int wave_s) {
;     ...
;             PG8_WAIT_V(8); PG8_WAIT_L(0); PG8_BAR; PG8_MMA(1, 0, At, B0); PG8_MMA(1, 1, At, B1); PG8_BAR; PG8_SCHED;
;             PG8_LDB(B0, 1, 0); PG8_LDB(B1, 1, 1); PG8_SCHED; PG8_LDA(At, 1, 0); PG8_STAGE(PG8_SA(0, 1), a2 + hstep, voffA);
;             PG8_WAIT_V(8); PG8_WAIT_L(0); PG8_BAR; PG8_MMA(0, 0, At, B0); PG8_MMA(0, 1, At, B1); PG8_BAR; PG8_SCHED;
	s_setprio 1
	v_mfma_f32_16x16x32_bf16 v[78:81], v[26:29], v[184:187], v[78:81]
	v_mfma_f32_16x16x32_bf16 v[74:77], v[46:49], v[184:187], v[74:77]
	v_mfma_f32_16x16x32_bf16 v[62:65], v[26:29], v[192:195], v[62:65]
	v_mfma_f32_16x16x32_bf16 v[58:61], v[46:49], v[192:195], v[58:61]
	v_mfma_f32_16x16x32_bf16 v[38:41], v[26:29], v[200:203], v[38:41]
	v_mfma_f32_16x16x32_bf16 v[34:37], v[46:49], v[200:203], v[34:37]
	v_mfma_f32_16x16x32_bf16 v[14:17], v[26:29], v[214:217], v[14:17]
	v_mfma_f32_16x16x32_bf16 v[10:13], v[46:49], v[214:217], v[10:13]
	v_mfma_f32_16x16x32_bf16 v[78:81], v[30:33], v[188:191], v[78:81]
	v_mfma_f32_16x16x32_bf16 v[74:77], v[50:53], v[188:191], v[74:77]
	v_mfma_f32_16x16x32_bf16 v[62:65], v[30:33], v[196:199], v[62:65]
	v_mfma_f32_16x16x32_bf16 v[58:61], v[50:53], v[196:199], v[58:61]
	v_mfma_f32_16x16x32_bf16 v[38:41], v[30:33], v[210:213], v[38:41]
	v_mfma_f32_16x16x32_bf16 v[34:37], v[50:53], v[210:213], v[34:37]
	v_mfma_f32_16x16x32_bf16 v[14:17], v[30:33], v[218:221], v[14:17]
	v_mfma_f32_16x16x32_bf16 v[10:13], v[50:53], v[218:221], v[10:13]
	s_setprio 0
	s_setprio 1
	v_mfma_f32_16x16x32_bf16 v[42:45], v[176:179], v[192:195], v[42:45]
	v_mfma_f32_16x16x32_bf16 v[22:25], v[162:165], v[200:203], v[22:25]
	v_mfma_f32_16x16x32_bf16 v[18:21], v[176:179], v[200:203], v[18:21]
	v_mfma_f32_16x16x32_bf16 v[6:9], v[162:165], v[214:217], v[6:9]
	v_mfma_f32_16x16x32_bf16 v[2:5], v[176:179], v[214:217], v[2:5]
	v_mfma_f32_16x16x32_bf16 v[26:29], v[162:165], v[184:187], v[70:73]
	v_mfma_f32_16x16x32_bf16 v[30:33], v[176:179], v[184:187], v[66:69]
	v_mfma_f32_16x16x32_bf16 v[46:49], v[162:165], v[192:195], v[54:57]
	v_mfma_f32_16x16x32_bf16 v[42:45], v[180:183], v[196:199], v[42:45]
	v_mfma_f32_16x16x32_bf16 v[22:25], v[166:169], v[210:213], v[22:25]
	v_mfma_f32_16x16x32_bf16 v[18:21], v[180:183], v[210:213], v[18:21]
	v_mfma_f32_16x16x32_bf16 v[6:9], v[166:169], v[218:221], v[6:9]
	v_mfma_f32_16x16x32_bf16 v[2:5], v[180:183], v[218:221], v[2:5]
	v_mfma_f32_16x16x32_bf16 v[26:29], v[166:169], v[188:191], v[26:29]
	v_mfma_f32_16x16x32_bf16 v[30:33], v[180:183], v[188:191], v[30:33]
	v_mfma_f32_16x16x32_bf16 v[46:49], v[166:169], v[196:199], v[46:49]
	s_setprio 0
	s_barrier
	s_add_i32 s45, 0, 0x18000
	s_add_i32 s64, 0, 0x1c000
	v_add_u32_e32 v70, s45, v171
	v_add_u32_e32 v175, s64, v171
	ds_read_b128 v[50:53], v70
	ds_read_b128 v[54:57], v70 offset:1024
	ds_read_b128 v[66:69], v70 offset:2048
	ds_read_b128 v[70:73], v70 offset:3072
	ds_read_b128 v[162:165], v175
	ds_read_b128 v[166:169], v175 offset:1024
	ds_read_b128 v[176:179], v175 offset:2048
	ds_read_b128 v[180:183], v175 offset:3072
	s_add_u32 s28, s28, 0x40000
	s_addc_u32 s29, s29, 0
	s_mov_b32 m0, s37
	v_lshl_add_u64 v[228:229], s[28:29], 0, v[0:1]
	ds_read_b128 v[184:187], v174 offset:32768
	ds_read_b128 v[188:191], v174 offset:33792
	ds_read_b128 v[192:195], v174 offset:34816
	ds_read_b128 v[196:199], v174 offset:35840
	ds_read_b128 v[200:203], v174 offset:36864
	ds_read_b128 v[210:213], v174 offset:37888
	ds_read_b128 v[214:217], v174 offset:38912
	ds_read_b128 v[218:221], v174 offset:39936
	global_load_lds_dwordx4 v[228:229], off
	v_lshl_add_u64 v[228:229], s[28:29], 0, v[146:147]
	s_mov_b32 m0, s38
	s_nop 0
	global_load_lds_dwordx4 v[228:229], off
	s_waitcnt vmcnt(8)
	s_waitcnt lgkmcnt(0)
	s_barrier
	s_setprio 1
	v_mfma_f32_16x16x32_bf16 v[142:145], v[50:53], v[184:187], v[142:145]
	v_mfma_f32_16x16x32_bf16 v[138:141], v[66:69], v[184:187], v[138:141]
	v_mfma_f32_16x16x32_bf16 v[126:129], v[50:53], v[192:195], v[126:129]
	v_mfma_f32_16x16x32_bf16 v[122:125], v[66:69], v[192:195], v[122:125]
	v_mfma_f32_16x16x32_bf16 v[110:113], v[50:53], v[200:203], v[110:113]
	v_mfma_f32_16x16x32_bf16 v[106:109], v[66:69], v[200:203], v[106:109]
	v_mfma_f32_16x16x32_bf16 v[94:97], v[50:53], v[214:217], v[94:97]
	v_mfma_f32_16x16x32_bf16 v[90:93], v[66:69], v[214:217], v[90:93]
	v_mfma_f32_16x16x32_bf16 v[142:145], v[54:57], v[188:191], v[142:145]
	v_mfma_f32_16x16x32_bf16 v[138:141], v[70:73], v[188:191], v[138:141]
	v_mfma_f32_16x16x32_bf16 v[126:129], v[54:57], v[196:199], v[126:129]
	v_mfma_f32_16x16x32_bf16 v[122:125], v[70:73], v[196:199], v[122:125]
	v_mfma_f32_16x16x32_bf16 v[110:113], v[54:57], v[210:213], v[110:113]
	v_mfma_f32_16x16x32_bf16 v[106:109], v[70:73], v[210:213], v[106:109]
	v_mfma_f32_16x16x32_bf16 v[94:97], v[54:57], v[218:221], v[94:97]
	v_mfma_f32_16x16x32_bf16 v[90:93], v[70:73], v[218:221], v[90:93]
	s_setprio 0
	s_setprio 1
	v_mfma_f32_16x16x32_bf16 v[134:137], v[162:165], v[184:187], v[134:137]
	v_mfma_f32_16x16x32_bf16 v[130:133], v[176:179], v[184:187], v[130:133]
	v_mfma_f32_16x16x32_bf16 v[118:121], v[162:165], v[192:195], v[118:121]
	v_mfma_f32_16x16x32_bf16 v[114:117], v[176:179], v[192:195], v[114:117]
	v_mfma_f32_16x16x32_bf16 v[102:105], v[162:165], v[200:203], v[102:105]
	v_mfma_f32_16x16x32_bf16 v[98:101], v[176:179], v[200:203], v[98:101]
	v_mfma_f32_16x16x32_bf16 v[86:89], v[162:165], v[214:217], v[86:89]
	v_mfma_f32_16x16x32_bf16 v[82:85], v[176:179], v[214:217], v[82:85]
	v_mfma_f32_16x16x32_bf16 v[134:137], v[166:169], v[188:191], v[134:137]
	v_mfma_f32_16x16x32_bf16 v[130:133], v[180:183], v[188:191], v[130:133]
	v_mfma_f32_16x16x32_bf16 v[118:121], v[166:169], v[196:199], v[118:121]
	v_mfma_f32_16x16x32_bf16 v[114:117], v[180:183], v[196:199], v[114:117]
	v_mfma_f32_16x16x32_bf16 v[102:105], v[166:169], v[210:213], v[102:105]
	v_mfma_f32_16x16x32_bf16 v[98:101], v[180:183], v[210:213], v[98:101]
	v_mfma_f32_16x16x32_bf16 v[86:89], v[166:169], v[218:221], v[86:89]
	v_mfma_f32_16x16x32_bf16 v[82:85], v[180:183], v[218:221], v[82:85]
	s_setprio 0
	s_barrier
; #define PG8_STAGE(bufoff, gbase, voff) do { _Pragma("unroll") for (int _i = 0; _i < 2; ++_i) \
;         __builtin_amdgcn_global_load_lds((const unsigned*)((const char*)(gbase) + (voff)[_i]), (PG8_LAS unsigned*)(lds + (bufoff) + ldsw + _i * 8192), 16, 0, 0); } while (0)
; #define PG8_LDA(dst, b, h) do { _Pragma("unroll") for (int m = 0; m < 4; ++m) _Pragma("unroll") for (int k = 0; k < 2; ++k) dst[m][k] = *(const PG8_LAS bf16x8*)(lds + PG8_SA(b, h) + aoff + m * 2048 + k * 1024); } while (0)
; #define PG8_BAR __builtin_amdgcn_s_barrier()
; template <class Epi, class Sched, bool ALIGN_EPI = false, bool SP2 = false>
; __device__ __forceinline__ void gemm_phase(PG8_LAS unsigned char* lds, const Gemm g, const Sched& S, const Epi& E, const int wave_s) {
;     ...
;             PG8_LDA(At, 1, 1); PG8_STAGE(PG8_SB(1, 0), b3, voffB); PG8_STAGE(PG8_SB(1, 1), b3 + hstep, voffB); PG8_STAGE(PG8_SA(1, 0), a3, voffA);
;             PG8_WAIT_V(8); PG8_WAIT_L(0); PG8_BAR; PG8_MMA(1, 0, At, B0); PG8_MMA(1, 1, At, B1); PG8_BAR; PG8_SCHED;
;             } else {
;             PG8_LDB(B0, 0, 0); PG8_SCHED; PG8_LDA(At, 0, 0); PG8_STAGE(PG8_SA(1, 1), a1 + hstep, voffA);
;             PG8_WAIT_L(8); PG8_BAR; PG8_WAIT_L(0); PG8_MMA(0, 0, At, B0); PG8_BAR; PG8_SCHED;
;             PG8_LDB(B1, 0, 1); PG8_STAGE(PG8_SB(0, 0), b2, voffB);
;             PG8_BAR; PG8_WAIT_L(0); PG8_MMA(0, 1, At, B1); PG8_BAR;
;             PG8_LDA(At, 0, 1); PG8_STAGE(PG8_SA(0, 0), a2, voffA);
;             PG8_BAR; PG8_WAIT_L(0); PG8_MMA(1, 0, At, B0); PG8_BAR; PG8_SCHED;
;             PG8_STAGE(PG8_SB(0, 1), b2 + hstep, voffB);
;             PG8_WAIT_V(6); PG8_BAR; PG8_MMA(1, 1, At, B1); PG8_BAR;
;             PG8_LDB(B0, 1, 0); PG8_SCHED; PG8_LDA(At, 1, 0); PG8_STAGE(PG8_SA(0, 1), a2 + hstep, voffA);
;             PG8_WAIT_L(8); PG8_BAR; PG8_WAIT_L(0); PG8_MMA(0, 0, At, B0); PG8_BAR; PG8_SCHED;
;             PG8_LDB(B1, 1, 1); PG8_STAGE(PG8_SB(1, 0), b3, voffB);
;             PG8_BAR; PG8_WAIT_L(0); PG8_MMA(0, 1, At, B1); PG8_BAR;
;             PG8_LDA(At, 1, 1); PG8_STAGE(PG8_SA(1, 0), a3, voffA);
;             PG8_BAR; PG8_WAIT_L(0); PG8_MMA(1, 0, At, B0); PG8_BAR; PG8_SCHED;
;             PG8_STAGE(PG8_SB(1, 1), b3 + hstep, voffB);
;             PG8_WAIT_V(6); PG8_BAR; PG8_MMA(1, 1, At, B1); PG8_BAR;
;             }
;         }
;         if constexpr (ALIGN_EPI) { if (wr == 0) PG8_BAR; }
	s_add_i32 s28, s45, s34
	v_lshl_add_u64 v[152:153], v[152:153], 0, s[70:71]
	s_mov_b32 m0, s28
	ds_read_b128 v[184:187], v174 offset:49152
	ds_read_b128 v[188:191], v174 offset:50176
	ds_read_b128 v[192:195], v174 offset:51200
	ds_read_b128 v[196:199], v174 offset:52224
	ds_read_b128 v[200:203], v174 offset:53248
	ds_read_b128 v[210:213], v174 offset:54272
	ds_read_b128 v[214:217], v174 offset:55296
	ds_read_b128 v[218:221], v174 offset:56320
	global_load_lds_dwordx4 v[152:153], off
	s_add_i32 m0, s28, 0x2000
	s_add_u32 s26, s26, 0x40080
	v_lshl_add_u64 v[152:153], v[222:223], 0, s[70:71]
	s_addc_u32 s27, s27, 0
	s_add_i32 s28, s64, s34
	global_load_lds_dwordx4 v[152:153], off
	v_lshl_add_u64 v[152:153], s[26:27], 0, v[0:1]
	s_mov_b32 m0, s28
	s_nop 0
	global_load_lds_dwordx4 v[152:153], off
	v_lshl_add_u64 v[152:153], s[26:27], 0, v[146:147]
	s_add_i32 m0, s28, 0x2000
	s_nop 0
	global_load_lds_dwordx4 v[152:153], off
	v_lshl_add_u64 v[152:153], v[224:225], 0, s[70:71]
	s_mov_b32 m0, s40
	s_nop 0
	global_load_lds_dwordx4 v[152:153], off
	v_lshl_add_u64 v[152:153], v[226:227], 0, s[70:71]
	s_mov_b32 m0, s41
	s_nop 0
	global_load_lds_dwordx4 v[152:153], off
	s_waitcnt vmcnt(8)
	s_waitcnt lgkmcnt(0)
	s_barrier
	s_setprio 1
	v_mfma_f32_16x16x32_bf16 v[78:81], v[50:53], v[184:187], v[78:81]
	v_mfma_f32_16x16x32_bf16 v[74:77], v[66:69], v[184:187], v[74:77]
	v_mfma_f32_16x16x32_bf16 v[62:65], v[50:53], v[192:195], v[62:65]
	v_mfma_f32_16x16x32_bf16 v[58:61], v[66:69], v[192:195], v[58:61]
	v_mfma_f32_16x16x32_bf16 v[38:41], v[50:53], v[200:203], v[38:41]
	v_mfma_f32_16x16x32_bf16 v[34:37], v[66:69], v[200:203], v[34:37]
	v_mfma_f32_16x16x32_bf16 v[14:17], v[50:53], v[214:217], v[14:17]
	v_mfma_f32_16x16x32_bf16 v[10:13], v[66:69], v[214:217], v[10:13]
	v_mfma_f32_16x16x32_bf16 v[78:81], v[54:57], v[188:191], v[78:81]
	v_mfma_f32_16x16x32_bf16 v[74:77], v[70:73], v[188:191], v[74:77]
	v_mfma_f32_16x16x32_bf16 v[62:65], v[54:57], v[196:199], v[62:65]
	v_mfma_f32_16x16x32_bf16 v[58:61], v[70:73], v[196:199], v[58:61]
	v_mfma_f32_16x16x32_bf16 v[38:41], v[54:57], v[210:213], v[38:41]
	v_mfma_f32_16x16x32_bf16 v[34:37], v[70:73], v[210:213], v[34:37]
	v_mfma_f32_16x16x32_bf16 v[14:17], v[54:57], v[218:221], v[14:17]
	v_mfma_f32_16x16x32_bf16 v[10:13], v[70:73], v[218:221], v[10:13]
	s_setprio 0
	s_setprio 1
	v_mfma_f32_16x16x32_bf16 v[26:29], v[162:165], v[184:187], v[26:29]
	v_mfma_f32_16x16x32_bf16 v[70:73], v[166:169], v[188:191], v[26:29]
	v_mfma_f32_16x16x32_bf16 v[26:29], v[176:179], v[184:187], v[30:33]
	v_mfma_f32_16x16x32_bf16 v[66:69], v[180:183], v[188:191], v[26:29]
	v_mfma_f32_16x16x32_bf16 v[26:29], v[162:165], v[192:195], v[46:49]
	v_mfma_f32_16x16x32_bf16 v[54:57], v[166:169], v[196:199], v[26:29]
	v_mfma_f32_16x16x32_bf16 v[26:29], v[176:179], v[192:195], v[42:45]
	v_mfma_f32_16x16x32_bf16 v[22:25], v[162:165], v[200:203], v[22:25]
	v_mfma_f32_16x16x32_bf16 v[18:21], v[176:179], v[200:203], v[18:21]
	v_mfma_f32_16x16x32_bf16 v[6:9], v[162:165], v[214:217], v[6:9]
	v_mfma_f32_16x16x32_bf16 v[2:5], v[176:179], v[214:217], v[2:5]
	v_mfma_f32_16x16x32_bf16 v[42:45], v[180:183], v[196:199], v[26:29]
	v_mfma_f32_16x16x32_bf16 v[22:25], v[166:169], v[210:213], v[22:25]
	v_mfma_f32_16x16x32_bf16 v[18:21], v[180:183], v[210:213], v[18:21]
	v_mfma_f32_16x16x32_bf16 v[6:9], v[166:169], v[218:221], v[6:9]
	v_mfma_f32_16x16x32_bf16 v[2:5], v[180:183], v[218:221], v[2:5]
	s_setprio 0
	s_barrier
	s_add_i32 s50, s50, 2
	s_add_u32 s24, s24, 0x100
	s_addc_u32 s25, s25, 0
	s_add_u32 s58, s58, 0x100
	s_addc_u32 s59, s59, 0
	s_cmp_gt_u32 s50, 13
	s_cbranch_scc0 .LBB0_734
	s_and_b64 vcc, exec, s[14:15]
	s_cbranch_vccz .LBB0_737
	s_barrier

; #define PG8_STAGE(bufoff, gbase, voff) do { _Pragma("unroll") for (int _i = 0; _i < 2; ++_i) \
;         __builtin_amdgcn_global_load_lds((const unsigned*)((const char*)(gbase) + (voff)[_i]), (PG8_LAS unsigned*)(lds + (bufoff) + ldsw + _i * 8192), 16, 0, 0); } while (0)
; #define PG8_LDA(dst, b, h) do { _Pragma("unroll") for (int m = 0; m < 4; ++m) _Pragma("unroll") for (int k = 0; k < 2; ++k) dst[m][k] = *(const PG8_LAS bf16x8*)(lds + PG8_SA(b, h) + aoff + m * 2048 + k * 1024); } while (0)
; #define PG8_LDB(dst, b, h) do { _Pragma("unroll") for (int n = 0; n < 2; ++n) _Pragma("unroll") for (int k = 0; k < 2; ++k) dst[n][k] = *(const PG8_LAS bf16x8*)(lds + PG8_SB(b, h) + boff + n * 2048 + k * 1024); } while (0)
; #define PG8_MMA(ai, bj, At, Bt) do { __builtin_amdgcn_s_setprio(1); _Pragma("unroll") for (int m = 0; m < 4; ++m) _Pragma("unroll") for (int n = 0; n < 2; ++n) _Pragma("unroll") for (int k = 0; k < 2; ++k) \
;         acc[ai][bj][m][n] = __builtin_amdgcn_mfma_f32_16x16x32_bf16(Bt[n][k], At[m][k], acc[ai][bj][m][n], 0, 0, 0); __builtin_amdgcn_s_setprio(0); } while (0)
; #define PG8_WAIT_V(n) asm volatile("s_waitcnt vmcnt(" #n ")" ::: "memory")
; #define PG8_WAIT_L(n) asm volatile("s_waitcnt lgkmcnt(" #n ")" ::: "memory")
; template <class Epi, class Sched, bool ALIGN_EPI = false, bool SP2 = false>
; __device__ __forceinline__ void gemm_phase(PG8_LAS unsigned char* lds, const Gemm g, const Sched& S, const Epi& E, const int wave_s) {
;     ...
;             const bool last = (t == nt - 2);
;             const char* a1 = cA + (size_t)(t + 1) * kstep;
;             const char* a2 = last ? nA : cA + (size_t)(t + 2) * kstep; const char* b2 = last ? nB : cB + (size_t)(t + 2) * kstep;
;             const char* a3 = a2 + kstep; const char* b3 = b2 + kstep;
;             if (last && has_next) S.a_ready(nxt);
;             if constexpr (SP2) {
;             PG8_LDB(B0, 0, 0); PG8_LDB(B1, 0, 1); PG8_SCHED; PG8_LDA(At, 0, 0); PG8_STAGE(PG8_SA(1, 1), a1 + hstep, voffA);
;             PG8_WAIT_V(8); PG8_WAIT_L(0); PG8_BAR; PG8_MMA(0, 0, At, B0); PG8_MMA(0, 1, At, B1); PG8_BAR; PG8_SCHED;
;             PG8_LDA(At, 0, 1); PG8_STAGE(PG8_SB(0, 0), b2, voffB); PG8_STAGE(PG8_SB(0, 1), b2 + hstep, voffB); PG8_STAGE(PG8_SA(0, 0), a2, voffA);
;             PG8_WAIT_V(8); PG8_WAIT_L(0); PG8_BAR; PG8_MMA(1, 0, At, B0); PG8_MMA(1, 1, At, B1); PG8_BAR; PG8_SCHED;
.LBB0_806:
	s_add_u32 s8, s10, 0x100
	s_addc_u32 s9, s11, 0
	s_add_i32 s45, 0, 0x10000
	s_cmp_eq_u32 s75, 40
	s_cselect_b32 s49, s37, s9
	s_cselect_b32 s48, s36, s8
	v_add_u32_e32 v0, s45, v203
	s_cselect_b32 s41, s39, vcc_hi
	s_cselect_b32 s40, s38, vcc_lo
	s_add_i32 s80, 0, 0x14000
	ds_read_b128 v[122:125], v0
	ds_read_b128 v[126:129], v0 offset:1024
	ds_read_b128 v[138:141], v0 offset:2048
	ds_read_b128 v[142:145], v0 offset:3072
	v_add_u32_e32 v0, s80, v203
	ds_read_b128 v[146:149], v0
	ds_read_b128 v[150:153], v0 offset:1024
	ds_read_b128 v[174:177], v0 offset:2048
	ds_read_b128 v[178:181], v0 offset:3072
	v_lshl_add_u64 v[226:227], s[10:11], 0, v[170:171]
	s_add_i32 m0, s76, 0xc000
	ds_read_b128 v[182:185], v212
	ds_read_b128 v[186:189], v212 offset:1024
	ds_read_b128 v[190:193], v212 offset:2048
	ds_read_b128 v[194:197], v212 offset:3072
	ds_read_b128 v[198:201], v212 offset:4096
	ds_read_b128 v[214:217], v212 offset:5120
	ds_read_b128 v[218:221], v212 offset:6144
	ds_read_b128 v[222:225], v212 offset:7168
	global_load_lds_dwordx4 v[226:227], off
	v_lshl_add_u64 v[226:227], s[10:11], 0, v[172:173]
	s_add_i32 m0, s76, 0xe000
	s_nop 0
	global_load_lds_dwordx4 v[226:227], off
	s_waitcnt vmcnt(8)
	s_waitcnt lgkmcnt(0)
	s_barrier
	s_setprio 1
	v_mfma_f32_16x16x32_bf16 v[6:9], v[122:125], v[182:185], v[6:9]
	v_mfma_f32_16x16x32_bf16 v[2:5], v[138:141], v[182:185], v[2:5]
	v_mfma_f32_16x16x32_bf16 v[134:137], v[122:125], v[190:193], v[134:137]
	v_mfma_f32_16x16x32_bf16 v[130:133], v[138:141], v[190:193], v[130:133]
	v_mfma_f32_16x16x32_bf16 v[118:121], v[122:125], v[198:201], v[118:121]
	v_mfma_f32_16x16x32_bf16 v[114:117], v[138:141], v[198:201], v[114:117]
	v_mfma_f32_16x16x32_bf16 v[110:113], v[122:125], v[218:221], v[110:113]
	v_mfma_f32_16x16x32_bf16 v[106:109], v[138:141], v[218:221], v[106:109]
	v_mfma_f32_16x16x32_bf16 v[6:9], v[126:129], v[186:189], v[6:9]
	v_mfma_f32_16x16x32_bf16 v[2:5], v[142:145], v[186:189], v[2:5]
	v_mfma_f32_16x16x32_bf16 v[134:137], v[126:129], v[194:197], v[134:137]
	v_mfma_f32_16x16x32_bf16 v[130:133], v[142:145], v[194:197], v[130:133]
	v_mfma_f32_16x16x32_bf16 v[118:121], v[126:129], v[214:217], v[118:121]
	v_mfma_f32_16x16x32_bf16 v[114:117], v[142:145], v[214:217], v[114:117]
	v_mfma_f32_16x16x32_bf16 v[110:113], v[126:129], v[222:225], v[110:113]
	v_mfma_f32_16x16x32_bf16 v[106:109], v[142:145], v[222:225], v[106:109]
	s_setprio 0
	s_setprio 1
	v_mfma_f32_16x16x32_bf16 v[70:73], v[146:149], v[182:185], v[70:73]
	v_mfma_f32_16x16x32_bf16 v[66:69], v[174:177], v[182:185], v[66:69]
	v_mfma_f32_16x16x32_bf16 v[62:65], v[146:149], v[190:193], v[62:65]
	v_mfma_f32_16x16x32_bf16 v[58:61], v[174:177], v[190:193], v[58:61]
	v_mfma_f32_16x16x32_bf16 v[54:57], v[146:149], v[198:201], v[54:57]
	v_mfma_f32_16x16x32_bf16 v[50:53], v[174:177], v[198:201], v[50:53]
	v_mfma_f32_16x16x32_bf16 v[46:49], v[146:149], v[218:221], v[46:49]
	v_mfma_f32_16x16x32_bf16 v[42:45], v[174:177], v[218:221], v[42:45]
	v_mfma_f32_16x16x32_bf16 v[70:73], v[150:153], v[186:189], v[70:73]
	v_mfma_f32_16x16x32_bf16 v[66:69], v[178:181], v[186:189], v[66:69]
	v_mfma_f32_16x16x32_bf16 v[62:65], v[150:153], v[194:197], v[62:65]
	v_mfma_f32_16x16x32_bf16 v[58:61], v[178:181], v[194:197], v[58:61]
	v_mfma_f32_16x16x32_bf16 v[54:57], v[150:153], v[214:217], v[54:57]
	v_mfma_f32_16x16x32_bf16 v[50:53], v[178:181], v[214:217], v[50:53]
	v_mfma_f32_16x16x32_bf16 v[46:49], v[150:153], v[222:225], v[46:49]
	v_mfma_f32_16x16x32_bf16 v[42:45], v[178:181], v[222:225], v[42:45]
	s_setprio 0
	s_barrier
	s_add_i32 s10, s45, s44
	v_lshl_add_u64 v[226:227], s[40:41], 0, v[166:167]
	s_mov_b32 m0, s10
	ds_read_b128 v[182:185], v212 offset:16384
	ds_read_b128 v[186:189], v212 offset:17408
	ds_read_b128 v[190:193], v212 offset:18432
	ds_read_b128 v[194:197], v212 offset:19456
	ds_read_b128 v[198:201], v212 offset:20480
	ds_read_b128 v[214:217], v212 offset:21504
	ds_read_b128 v[218:221], v212 offset:22528
	ds_read_b128 v[222:225], v212 offset:23552
	global_load_lds_dwordx4 v[226:227], off
	s_add_i32 m0, s10, 0x2000
	s_add_u32 s10, s40, 0xb0000
	v_lshl_add_u64 v[228:229], s[40:41], 0, v[162:163]
	s_addc_u32 s11, s41, 0
	s_add_i32 s45, s80, s44
	global_load_lds_dwordx4 v[228:229], off
	v_lshl_add_u64 v[230:231], s[10:11], 0, v[166:167]
	s_mov_b32 m0, s45
	v_lshl_add_u64 v[232:233], s[48:49], 0, v[164:165]
	global_load_lds_dwordx4 v[230:231], off
	v_lshl_add_u64 v[230:231], s[10:11], 0, v[162:163]
	s_add_i32 m0, s45, 0x2000
	s_nop 0
	global_load_lds_dwordx4 v[230:231], off
	v_lshl_add_u64 v[230:231], s[48:49], 0, v[168:169]
	s_mov_b32 m0, s76
	s_nop 0
	global_load_lds_dwordx4 v[230:231], off
	s_mov_b32 m0, s77
	s_nop 0
	global_load_lds_dwordx4 v[232:233], off
	s_waitcnt vmcnt(8)
	s_waitcnt lgkmcnt(0)
	s_barrier
; #define PG8_STAGE(bufoff, gbase, voff) do { _Pragma("unroll") for (int _i = 0; _i < 2; ++_i) \
;         __builtin_amdgcn_global_load_lds((const unsigned*)((const char*)(gbase) + (voff)[_i]), (PG8_LAS unsigned*)(lds + (bufoff) + ldsw + _i * 8192), 16, 0, 0); } while (0)
; #define PG8_LDA(dst, b, h) do { _Pragma("unroll") for (int m = 0; m < 4; ++m) _Pragma("unroll") for (int k = 0; k < 2; ++k) dst[m][k] = *(const PG8_LAS bf16x8*)(lds + PG8_SA(b, h) + aoff + m * 2048 + k * 1024); } while (0)
; #define PG8_LDB(dst, b, h) do { _Pragma("unroll") for (int n = 0; n < 2; ++n) _Pragma("unroll") for (int k = 0; k < 2; ++k) dst[n][k] = *(const PG8_LAS bf16x8*)(lds + PG8_SB(b, h) + boff + n * 2048 + k * 1024); } while (0)
; #define PG8_MMA(ai, bj, At, Bt) do { __builtin_amdgcn_s_setprio(1); _Pragma("unroll") for (int m = 0; m < 4; ++m) _Pragma("unroll") for (int n = 0; n < 2; ++n) _Pragma("unroll") for (int k = 0; k < 2; ++k) \
;         acc[ai][bj][m][n] = __builtin_amdgcn_mfma_f32_16x16x32_bf16(Bt[n][k], At[m][k], acc[ai][bj][m][n], 0, 0, 0); __builtin_amdgcn_s_setprio(0); } while (0)
; #define PG8_WAIT_V(n) asm volatile("s_waitcnt vmcnt(" #n ")" ::: "memory")
; #define PG8_WAIT_L(n) asm volatile("s_waitcnt lgkmcnt(" #n ")" ::: "memory")
; #define PG8_BAR __builtin_amdgcn_s_barrier()
; #define PG8_SCHED __builtin_amdgcn_sched_barrier(0)
; template <class Epi, class Sched, bool ALIGN_EPI = false, bool SP2 = false>
; __device__ __forceinline__ void gemm_phase(PG8_LAS unsigned char* lds, const Gemm g, const Sched& S, const Epi& E, const int wave_s) {
;     ...
;             PG8_WAIT_V(8); PG8_WAIT_L(0); PG8_BAR; PG8_MMA(1, 0, At, B0); PG8_MMA(1, 1, At, B1); PG8_BAR; PG8_SCHED;
;             PG8_LDB(B0, 1, 0); PG8_LDB(B1, 1, 1); PG8_SCHED; PG8_LDA(At, 1, 0); PG8_STAGE(PG8_SA(0, 1), a2 + hstep, voffA);
;             PG8_WAIT_V(8); PG8_WAIT_L(0); PG8_BAR; PG8_MMA(0, 0, At, B0); PG8_MMA(0, 1, At, B1); PG8_BAR; PG8_SCHED;
	s_setprio 1
	v_mfma_f32_16x16x32_bf16 v[102:105], v[122:125], v[182:185], v[102:105]
	v_mfma_f32_16x16x32_bf16 v[98:101], v[138:141], v[182:185], v[98:101]
	v_mfma_f32_16x16x32_bf16 v[94:97], v[122:125], v[190:193], v[94:97]
	v_mfma_f32_16x16x32_bf16 v[90:93], v[138:141], v[190:193], v[90:93]
	v_mfma_f32_16x16x32_bf16 v[86:89], v[122:125], v[198:201], v[86:89]
	v_mfma_f32_16x16x32_bf16 v[82:85], v[138:141], v[198:201], v[82:85]
	v_mfma_f32_16x16x32_bf16 v[78:81], v[122:125], v[218:221], v[78:81]
	v_mfma_f32_16x16x32_bf16 v[74:77], v[138:141], v[218:221], v[74:77]
	v_mfma_f32_16x16x32_bf16 v[102:105], v[126:129], v[186:189], v[102:105]
	v_mfma_f32_16x16x32_bf16 v[98:101], v[142:145], v[186:189], v[98:101]
	v_mfma_f32_16x16x32_bf16 v[94:97], v[126:129], v[194:197], v[94:97]
	v_mfma_f32_16x16x32_bf16 v[90:93], v[142:145], v[194:197], v[90:93]
	v_mfma_f32_16x16x32_bf16 v[86:89], v[126:129], v[214:217], v[86:89]
	v_mfma_f32_16x16x32_bf16 v[82:85], v[142:145], v[214:217], v[82:85]
	v_mfma_f32_16x16x32_bf16 v[78:81], v[126:129], v[222:225], v[78:81]
	v_mfma_f32_16x16x32_bf16 v[74:77], v[142:145], v[222:225], v[74:77]
	s_setprio 0
	s_setprio 1
	v_mfma_f32_16x16x32_bf16 v[38:41], v[146:149], v[182:185], v[38:41]
	v_mfma_f32_16x16x32_bf16 v[34:37], v[174:177], v[182:185], v[34:37]
	v_mfma_f32_16x16x32_bf16 v[30:33], v[146:149], v[190:193], v[30:33]
	v_mfma_f32_16x16x32_bf16 v[26:29], v[174:177], v[190:193], v[26:29]
	v_mfma_f32_16x16x32_bf16 v[22:25], v[146:149], v[198:201], v[22:25]
	v_mfma_f32_16x16x32_bf16 v[18:21], v[174:177], v[198:201], v[18:21]
	v_mfma_f32_16x16x32_bf16 v[14:17], v[146:149], v[218:221], v[14:17]
	v_mfma_f32_16x16x32_bf16 v[10:13], v[174:177], v[218:221], v[10:13]
	v_mfma_f32_16x16x32_bf16 v[38:41], v[150:153], v[186:189], v[38:41]
	v_mfma_f32_16x16x32_bf16 v[34:37], v[178:181], v[186:189], v[34:37]
	v_mfma_f32_16x16x32_bf16 v[30:33], v[150:153], v[194:197], v[30:33]
	v_mfma_f32_16x16x32_bf16 v[26:29], v[178:181], v[194:197], v[26:29]
	v_mfma_f32_16x16x32_bf16 v[22:25], v[150:153], v[214:217], v[22:25]
	v_mfma_f32_16x16x32_bf16 v[18:21], v[178:181], v[214:217], v[18:21]
	v_mfma_f32_16x16x32_bf16 v[14:17], v[150:153], v[222:225], v[14:17]
	v_mfma_f32_16x16x32_bf16 v[10:13], v[178:181], v[222:225], v[10:13]
	s_setprio 0
	s_barrier
	s_add_i32 s45, 0, 0x18000
	v_add_u32_e32 v0, s45, v203
	s_add_i32 s80, 0, 0x1c000
	ds_read_b128 v[122:125], v0
	ds_read_b128 v[126:129], v0 offset:1024
	ds_read_b128 v[138:141], v0 offset:2048
	ds_read_b128 v[142:145], v0 offset:3072
	v_add_u32_e32 v0, s80, v203
	ds_read_b128 v[146:149], v0
	ds_read_b128 v[150:153], v0 offset:1024
	ds_read_b128 v[174:177], v0 offset:2048
	ds_read_b128 v[178:181], v0 offset:3072
	s_add_u32 s10, s48, 0xb0000
	s_addc_u32 s11, s49, 0
	s_mov_b32 m0, s88
	v_lshl_add_u64 v[234:235], s[10:11], 0, v[168:169]
	ds_read_b128 v[182:185], v212 offset:32768
	ds_read_b128 v[186:189], v212 offset:33792
	ds_read_b128 v[190:193], v212 offset:34816
	ds_read_b128 v[194:197], v212 offset:35840
	ds_read_b128 v[198:201], v212 offset:36864
	ds_read_b128 v[214:217], v212 offset:37888
	ds_read_b128 v[218:221], v212 offset:38912
	ds_read_b128 v[222:225], v212 offset:39936
	global_load_lds_dwordx4 v[234:235], off
	v_lshl_add_u64 v[234:235], s[10:11], 0, v[164:165]
	s_mov_b32 m0, s89
	s_nop 0
	global_load_lds_dwordx4 v[234:235], off
	s_waitcnt vmcnt(8)
	s_waitcnt lgkmcnt(0)
	s_barrier
	s_setprio 1
	v_mfma_f32_16x16x32_bf16 v[6:9], v[122:125], v[182:185], v[6:9]
	v_mfma_f32_16x16x32_bf16 v[2:5], v[138:141], v[182:185], v[2:5]
	v_mfma_f32_16x16x32_bf16 v[134:137], v[122:125], v[190:193], v[134:137]
	v_mfma_f32_16x16x32_bf16 v[130:133], v[138:141], v[190:193], v[130:133]
	v_mfma_f32_16x16x32_bf16 v[118:121], v[122:125], v[198:201], v[118:121]
	v_mfma_f32_16x16x32_bf16 v[114:117], v[138:141], v[198:201], v[114:117]
	v_mfma_f32_16x16x32_bf16 v[110:113], v[122:125], v[218:221], v[110:113]
	v_mfma_f32_16x16x32_bf16 v[106:109], v[138:141], v[218:221], v[106:109]
	v_mfma_f32_16x16x32_bf16 v[6:9], v[126:129], v[186:189], v[6:9]
	v_mfma_f32_16x16x32_bf16 v[2:5], v[142:145], v[186:189], v[2:5]
	v_mfma_f32_16x16x32_bf16 v[134:137], v[126:129], v[194:197], v[134:137]
	v_mfma_f32_16x16x32_bf16 v[130:133], v[142:145], v[194:197], v[130:133]
	v_mfma_f32_16x16x32_bf16 v[118:121], v[126:129], v[214:217], v[118:121]
	v_mfma_f32_16x16x32_bf16 v[114:117], v[142:145], v[214:217], v[114:117]
	v_mfma_f32_16x16x32_bf16 v[110:113], v[126:129], v[222:225], v[110:113]
	v_mfma_f32_16x16x32_bf16 v[106:109], v[142:145], v[222:225], v[106:109]
	s_setprio 0
	s_setprio 1
	v_mfma_f32_16x16x32_bf16 v[70:73], v[146:149], v[182:185], v[70:73]
	v_mfma_f32_16x16x32_bf16 v[66:69], v[174:177], v[182:185], v[66:69]
	v_mfma_f32_16x16x32_bf16 v[62:65], v[146:149], v[190:193], v[62:65]
	v_mfma_f32_16x16x32_bf16 v[58:61], v[174:177], v[190:193], v[58:61]
	v_mfma_f32_16x16x32_bf16 v[54:57], v[146:149], v[198:201], v[54:57]
	v_mfma_f32_16x16x32_bf16 v[50:53], v[174:177], v[198:201], v[50:53]
	v_mfma_f32_16x16x32_bf16 v[46:49], v[146:149], v[218:221], v[46:49]
	v_mfma_f32_16x16x32_bf16 v[42:45], v[174:177], v[218:221], v[42:45]
	v_mfma_f32_16x16x32_bf16 v[70:73], v[150:153], v[186:189], v[70:73]
	v_mfma_f32_16x16x32_bf16 v[66:69], v[178:181], v[186:189], v[66:69]
	v_mfma_f32_16x16x32_bf16 v[62:65], v[150:153], v[194:197], v[62:65]
	v_mfma_f32_16x16x32_bf16 v[58:61], v[178:181], v[194:197], v[58:61]
	v_mfma_f32_16x16x32_bf16 v[54:57], v[150:153], v[214:217], v[54:57]
	v_mfma_f32_16x16x32_bf16 v[50:53], v[178:181], v[214:217], v[50:53]
	v_mfma_f32_16x16x32_bf16 v[46:49], v[150:153], v[222:225], v[46:49]
	v_mfma_f32_16x16x32_bf16 v[42:45], v[178:181], v[222:225], v[42:45]
	s_setprio 0
	s_barrier
; #define PG8_STAGE(bufoff, gbase, voff) do { _Pragma("unroll") for (int _i = 0; _i < 2; ++_i) \
;         __builtin_amdgcn_global_load_lds((const unsigned*)((const char*)(gbase) + (voff)[_i]), (PG8_LAS unsigned*)(lds + (bufoff) + ldsw + _i * 8192), 16, 0, 0); } while (0)
; #define PG8_LDA(dst, b, h) do { _Pragma("unroll") for (int m = 0; m < 4; ++m) _Pragma("unroll") for (int k = 0; k < 2; ++k) dst[m][k] = *(const PG8_LAS bf16x8*)(lds + PG8_SA(b, h) + aoff + m * 2048 + k * 1024); } while (0)
; #define PG8_BAR __builtin_amdgcn_s_barrier()
; template <class Epi, class Sched, bool ALIGN_EPI = false, bool SP2 = false>
; __device__ __forceinline__ void gemm_phase(PG8_LAS unsigned char* lds, const Gemm g, const Sched& S, const Epi& E, const int wave_s) {
;     ...
;             PG8_LDA(At, 1, 1); PG8_STAGE(PG8_SB(1, 0), b3, voffB); PG8_STAGE(PG8_SB(1, 1), b3 + hstep, voffB); PG8_STAGE(PG8_SA(1, 0), a3, voffA);
;             PG8_WAIT_V(8); PG8_WAIT_L(0); PG8_BAR; PG8_MMA(1, 0, At, B0); PG8_MMA(1, 1, At, B1); PG8_BAR; PG8_SCHED;
;             } else {
;             PG8_LDB(B0, 0, 0); PG8_SCHED; PG8_LDA(At, 0, 0); PG8_STAGE(PG8_SA(1, 1), a1 + hstep, voffA);
;             PG8_WAIT_L(8); PG8_BAR; PG8_WAIT_L(0); PG8_MMA(0, 0, At, B0); PG8_BAR; PG8_SCHED;
;             PG8_LDB(B1, 0, 1); PG8_STAGE(PG8_SB(0, 0), b2, voffB);
;             PG8_BAR; PG8_WAIT_L(0); PG8_MMA(0, 1, At, B1); PG8_BAR;
;             PG8_LDA(At, 0, 1); PG8_STAGE(PG8_SA(0, 0), a2, voffA);
;             PG8_BAR; PG8_WAIT_L(0); PG8_MMA(1, 0, At, B0); PG8_BAR; PG8_SCHED;
;             PG8_STAGE(PG8_SB(0, 1), b2 + hstep, voffB);
;             PG8_WAIT_V(6); PG8_BAR; PG8_MMA(1, 1, At, B1); PG8_BAR;
;             PG8_LDB(B0, 1, 0); PG8_SCHED; PG8_LDA(At, 1, 0); PG8_STAGE(PG8_SA(0, 1), a2 + hstep, voffA);
;             PG8_WAIT_L(8); PG8_BAR; PG8_WAIT_L(0); PG8_MMA(0, 0, At, B0); PG8_BAR; PG8_SCHED;
;             PG8_LDB(B1, 1, 1); PG8_STAGE(PG8_SB(1, 0), b3, voffB);
;             PG8_BAR; PG8_WAIT_L(0); PG8_MMA(0, 1, At, B1); PG8_BAR;
;             PG8_LDA(At, 1, 1); PG8_STAGE(PG8_SA(1, 0), a3, voffA);
;             PG8_BAR; PG8_WAIT_L(0); PG8_MMA(1, 0, At, B0); PG8_BAR; PG8_SCHED;
;             PG8_STAGE(PG8_SB(1, 1), b3 + hstep, voffB);
;             PG8_WAIT_V(6); PG8_BAR; PG8_MMA(1, 1, At, B1); PG8_BAR;
;             }
;         }
;         if constexpr (ALIGN_EPI) { if (wr == 0) PG8_BAR; }
	s_add_i32 s10, s45, s44
	v_lshl_add_u64 v[226:227], v[226:227], 0, s[70:71]
	s_mov_b32 m0, s10
	ds_read_b128 v[182:185], v212 offset:49152
	ds_read_b128 v[186:189], v212 offset:50176
	ds_read_b128 v[190:193], v212 offset:51200
	ds_read_b128 v[194:197], v212 offset:52224
	ds_read_b128 v[198:201], v212 offset:53248
	ds_read_b128 v[214:217], v212 offset:54272
	ds_read_b128 v[218:221], v212 offset:55296
	ds_read_b128 v[222:225], v212 offset:56320
	global_load_lds_dwordx4 v[226:227], off
	s_add_i32 m0, s10, 0x2000
	s_add_u32 s10, s40, 0xb0080
	v_lshl_add_u64 v[226:227], v[228:229], 0, s[70:71]
	s_addc_u32 s11, s41, 0
	s_add_i32 s40, s80, s44
	global_load_lds_dwordx4 v[226:227], off
	v_lshl_add_u64 v[226:227], s[10:11], 0, v[166:167]
	s_mov_b32 m0, s40
	s_nop 0
	global_load_lds_dwordx4 v[226:227], off
	v_lshl_add_u64 v[226:227], s[10:11], 0, v[162:163]
	s_add_i32 m0, s40, 0x2000
	s_nop 0
	global_load_lds_dwordx4 v[226:227], off
	v_lshl_add_u64 v[226:227], v[230:231], 0, s[70:71]
	s_mov_b32 m0, s62
	s_nop 0
	global_load_lds_dwordx4 v[226:227], off
	v_lshl_add_u64 v[226:227], v[232:233], 0, s[70:71]
	s_mov_b32 m0, s68
	s_nop 0
	global_load_lds_dwordx4 v[226:227], off
	s_waitcnt vmcnt(8)
	s_waitcnt lgkmcnt(0)
	s_barrier
	s_setprio 1
	v_mfma_f32_16x16x32_bf16 v[102:105], v[122:125], v[182:185], v[102:105]
	v_mfma_f32_16x16x32_bf16 v[98:101], v[138:141], v[182:185], v[98:101]
	v_mfma_f32_16x16x32_bf16 v[94:97], v[122:125], v[190:193], v[94:97]
	v_mfma_f32_16x16x32_bf16 v[90:93], v[138:141], v[190:193], v[90:93]
	v_mfma_f32_16x16x32_bf16 v[86:89], v[122:125], v[198:201], v[86:89]
	v_mfma_f32_16x16x32_bf16 v[82:85], v[138:141], v[198:201], v[82:85]
	v_mfma_f32_16x16x32_bf16 v[78:81], v[122:125], v[218:221], v[78:81]
	v_mfma_f32_16x16x32_bf16 v[74:77], v[138:141], v[218:221], v[74:77]
	v_mfma_f32_16x16x32_bf16 v[102:105], v[126:129], v[186:189], v[102:105]
	v_mfma_f32_16x16x32_bf16 v[98:101], v[142:145], v[186:189], v[98:101]
	v_mfma_f32_16x16x32_bf16 v[94:97], v[126:129], v[194:197], v[94:97]
	v_mfma_f32_16x16x32_bf16 v[90:93], v[142:145], v[194:197], v[90:93]
	v_mfma_f32_16x16x32_bf16 v[86:89], v[126:129], v[214:217], v[86:89]
	v_mfma_f32_16x16x32_bf16 v[82:85], v[142:145], v[214:217], v[82:85]
	v_mfma_f32_16x16x32_bf16 v[78:81], v[126:129], v[222:225], v[78:81]
	v_mfma_f32_16x16x32_bf16 v[74:77], v[142:145], v[222:225], v[74:77]
	s_setprio 0
	s_setprio 1
	v_mfma_f32_16x16x32_bf16 v[38:41], v[146:149], v[182:185], v[38:41]
	v_mfma_f32_16x16x32_bf16 v[34:37], v[174:177], v[182:185], v[34:37]
	v_mfma_f32_16x16x32_bf16 v[30:33], v[146:149], v[190:193], v[30:33]
	v_mfma_f32_16x16x32_bf16 v[26:29], v[174:177], v[190:193], v[26:29]
	v_mfma_f32_16x16x32_bf16 v[22:25], v[146:149], v[198:201], v[22:25]
	v_mfma_f32_16x16x32_bf16 v[18:21], v[174:177], v[198:201], v[18:21]
	v_mfma_f32_16x16x32_bf16 v[14:17], v[146:149], v[218:221], v[14:17]
	v_mfma_f32_16x16x32_bf16 v[10:13], v[174:177], v[218:221], v[10:13]
	v_mfma_f32_16x16x32_bf16 v[38:41], v[150:153], v[186:189], v[38:41]
	v_mfma_f32_16x16x32_bf16 v[34:37], v[178:181], v[186:189], v[34:37]
	v_mfma_f32_16x16x32_bf16 v[30:33], v[150:153], v[194:197], v[30:33]
	v_mfma_f32_16x16x32_bf16 v[26:29], v[178:181], v[194:197], v[26:29]
	v_mfma_f32_16x16x32_bf16 v[22:25], v[150:153], v[214:217], v[22:25]
	v_mfma_f32_16x16x32_bf16 v[18:21], v[178:181], v[214:217], v[18:21]
	v_mfma_f32_16x16x32_bf16 v[14:17], v[150:153], v[222:225], v[14:17]
	v_mfma_f32_16x16x32_bf16 v[10:13], v[178:181], v[222:225], v[10:13]
	s_setprio 0
	s_barrier
	s_add_i32 s75, s75, 2
	s_add_u32 vcc_lo, vcc_lo, 0x100
	s_addc_u32 vcc_hi, vcc_hi, 0
	s_cmp_gt_u32 s75, 41
	s_mov_b64 s[10:11], s[8:9]
	s_cbranch_scc0 .LBB0_806
	s_and_b64 vcc, exec, s[28:29]
	s_cbranch_vccz .LBB0_809
	s_barrier
